# gate/up context-row tiles (64x128): 5-slot BK=32 LDS ring with prefetch distance 4
# baseline (speedup 1.0000x reference)
; #define TIDX opaque_tid()
; template <int AI>
; DI void gu_tile(char* wsb, int sub, int m0, int n0, char* lds) {
;   const u16* H = (const u16*)(wsb + OFF_H);
;   const u16* W = (const u16*)(wsb + OFF_W) + (sub ? W_GU1 : W_GU0);
;   u16* HID = (u16*)(wsb + OFF_HID);
;   const int lane = TIDX & 63, wid = TIDX >> 6, wa = wid >> 1, wb = wid & 1, r = lane & 31, h = lane >> 5;
;   f32x16 acc[AI][2]; zero_acc<AI, 2>(acc);
;   gemm_tile<AI, 2>(H + (size_t)m0 * 1024, 1024, W + (size_t)n0 * 1024, 1024, 16, false, acc, lds);
; DI void phase_gu(const Params& p, char* wsb, int sub, int mrows, char* lds) {
;     ...
;   for (int rnd = 0; next_tile(rnd, 128, 44, mt, nt); ++rnd) gu_tile<2>(wsb, sub, mt * 128, nt * 128, lds);
;   if (mrows > TL)
;     for (int rnd = 0; next_tile(rnd, 32, 44, mt, nt); ++rnd) gu_tile<1>(wsb, sub, TL + mt * 64, nt * 128, lds);
.LBB0_421:
	v_readlane_b32 s6, v244, 50
	v_readlane_b32 s7, v244, 51
	s_andn2_b64 vcc, exec, s[6:7]
	s_mov_b32 s49, 0x1ffffe0
	s_cbranch_vccnz .LBB0_425
	s_add_u32 s10, s8, 0x77b7000
	s_addc_u32 s11, s9, 0
	s_add_u32 s12, s8, 0x1c4b7000
	s_addc_u32 s13, s9, 0
	s_add_u32 s6, s8, 0x9bb7000
	s_addc_u32 s7, s9, 0
	v_readlane_b32 s14, v243, 18
	v_readlane_b32 s15, v243, 10
	v_readlane_b32 s16, v243, 8
	v_readlane_b32 s48, v243, 7
	s_mov_b64 s[50:51], 0x200
	s_mov_b64 s[52:53], 0x80
	s_mov_b64 s[54:55], 0x180
	s_mov_b64 s[64:65], 0x300
	s_mov_b64 s[66:67], 0x380
	s_mov_b64 s[68:69], 0x400
	s_mov_b64 s[70:71], 0x480
	s_mov_b64 s[72:73], 0x500
	s_mov_b64 s[74:75], 0x580
	s_mov_b64 s[76:77], 0x600
	s_mov_b64 s[56:57], 0x280
	s_cmpk_lg_u32 s92, 0x200
	s_cbranch_scc1 .LBB0_423
	v_and_b32_e32 v70, 31, v178
	v_bfe_u32 v71, v178, 5, 1
	v_bfe_u32 v72, v178, 2, 2
	v_xor_b32_e32 v71, v71, v72
	v_lshlrev_b32_e32 v71, 4, v71
	v_bfe_u32 v72, v178, 7, 1
	v_lshl_add_u32 v72, v72, 5, v70
	v_lshl_add_u32 v58, v72, 6, v71
	v_xor_b32_e32 v59, 32, v58
	v_bfe_u32 v72, v178, 6, 1
	v_lshl_add_u32 v72, v72, 6, v70
	v_lshl_add_u32 v60, v72, 6, v71
	v_add_u32_e32 v60, 0x1000, v60
	v_xor_b32_e32 v61, 32, v60
	v_bfe_u32 v71, v178, 7, 1
	v_lshlrev_b32_e32 v71, 5, v71
	v_bfe_u32 v72, v178, 5, 1
	v_lshl_add_u32 v71, v72, 2, v71
	v_mul_u32_u24_e32 v71, 0xb00, v71
	v_bfe_u32 v72, v178, 6, 1
	v_lshl_add_u32 v72, v72, 5, v70
	v_add_u32_e32 v71, v71, v72
	v_lshlrev_b32_e32 v64, 1, v71
	v_lshrrev_b32_e32 v70, 2, v178
	v_bfe_u32 v71, v178, 4, 2
	v_and_b32_e32 v72, 3, v178
	v_xor_b32_e32 v71, v71, v72
	v_lshlrev_b32_e32 v71, 4, v71
	v_lshl_add_u32 v62, v70, 11, v71
	v_add_u32_e32 v63, 0x20000, v62
	v_lshrrev_b32_e32 v70, 6, v178
	s_nop 1
	v_readfirstlane_b32 s17, v70
	s_lshl_b32 s17, s17, 10
	s_mov_b32 s36, s14
.Lgc1_tile:
	s_mul_i32 s37, s36, 0xba2f
	s_lshr_b32 s37, s37, 24
	s_mul_i32 s40, s37, 0x160
	s_sub_u32 s40, s36, s40
	s_lshr_b32 s41, s40, 3
	s_and_b32 s40, s40, 7
	s_lshl_b32 s37, s37, 3
	s_or_b32 s37, s37, s40
	s_lshl_b32 s37, s37, 6
	s_bitset1_b32 s37, 14
	s_lshl_b32 s46, s37, 11
	s_add_u32 s8, s10, s46
	s_addc_u32 s9, s11, 0
	s_lshl_b32 s46, s41, 18
	s_add_u32 s28, s12, s46
	s_addc_u32 s29, s13, 0
	s_mul_i32 s46, s37, 0x1600
	s_lshl_b32 s47, s41, 7
	s_add_u32 s46, s46, s47
	s_add_u32 s34, s6, s46
	s_addc_u32 s35, s7, 0
	s_barrier
	v_mov_b32_e32 v2, 0
	v_mov_b32_e32 v3, 0
	v_mov_b32_e32 v4, 0
	v_mov_b32_e32 v5, 0
	v_mov_b32_e32 v6, 0
	v_mov_b32_e32 v7, 0
	v_mov_b32_e32 v8, 0
	v_mov_b32_e32 v9, 0
	v_mov_b32_e32 v10, 0
	v_mov_b32_e32 v11, 0
	v_mov_b32_e32 v12, 0
	v_mov_b32_e32 v13, 0
	v_mov_b32_e32 v14, 0
	v_mov_b32_e32 v15, 0
	v_mov_b32_e32 v16, 0
	v_mov_b32_e32 v17, 0
	v_mov_b32_e32 v18, 0
	v_mov_b32_e32 v19, 0
	v_mov_b32_e32 v20, 0
	v_mov_b32_e32 v21, 0
	v_mov_b32_e32 v22, 0
	v_mov_b32_e32 v23, 0
	v_mov_b32_e32 v24, 0
	v_mov_b32_e32 v25, 0
	v_mov_b32_e32 v26, 0
	v_mov_b32_e32 v27, 0
	v_mov_b32_e32 v28, 0
	v_mov_b32_e32 v29, 0
	v_mov_b32_e32 v30, 0
	v_mov_b32_e32 v31, 0
	v_mov_b32_e32 v32, 0
	v_mov_b32_e32 v33, 0
	s_add_u32 m0, s17, 0
	s_nop 0
	global_load_lds_dwordx4 v62, s[8:9]
	s_add_u32 m0, s17, 4096
	s_nop 0
	global_load_lds_dwordx4 v62, s[28:29]
	s_add_u32 m0, s17, 8192
	s_nop 0
	global_load_lds_dwordx4 v63, s[28:29]
	s_add_u32 s8, s8, 64
	s_addc_u32 s9, s9, 0
	s_add_u32 s28, s28, 64
	s_addc_u32 s29, s29, 0
	s_add_u32 m0, s17, 12288
	s_nop 0
	global_load_lds_dwordx4 v62, s[8:9]
	s_add_u32 m0, s17, 16384
	s_nop 0
	global_load_lds_dwordx4 v62, s[28:29]
	s_add_u32 m0, s17, 20480
	s_nop 0
	global_load_lds_dwordx4 v63, s[28:29]
	s_add_u32 s8, s8, 64
	s_addc_u32 s9, s9, 0
	s_add_u32 s28, s28, 64
	s_addc_u32 s29, s29, 0
	s_add_u32 m0, s17, 24576
	s_nop 0
	global_load_lds_dwordx4 v62, s[8:9]
	s_add_u32 m0, s17, 28672
	s_nop 0
	global_load_lds_dwordx4 v62, s[28:29]
	s_add_u32 m0, s17, 32768
	s_nop 0
	global_load_lds_dwordx4 v63, s[28:29]
	s_add_u32 s8, s8, 64
	s_addc_u32 s9, s9, 0
	s_add_u32 s28, s28, 64
	s_addc_u32 s29, s29, 0
	s_add_u32 m0, s17, 36864
	s_nop 0
	global_load_lds_dwordx4 v62, s[8:9]
	s_add_u32 m0, s17, 40960
	s_nop 0
	global_load_lds_dwordx4 v62, s[28:29]
	s_add_u32 m0, s17, 45056
	s_nop 0
	global_load_lds_dwordx4 v63, s[28:29]
	s_add_u32 s8, s8, 64
	s_addc_u32 s9, s9, 0
	s_add_u32 s28, s28, 64
	s_addc_u32 s29, s29, 0
	s_mov_b32 s18, 5
; #define MFMA(a, b, c) __builtin_amdgcn_mfma_f32_32x32x16_bf16((a), (b), (c), 0, 0, 0)
; template <int AI, int BI>
; DI void gemm_tile(const u16* __restrict__ A, int lda, const u16* __restrict__ B, int ldb, int nk, bool swap,
;                   f32x16 (&acc)[AI][BI], char* lds) {
;     ...
;   for (int kt = 0; kt < nk; ++kt) {
;     const char* cur = lds + (kt & 1) * 32768;
;     if (kt + 1 < nk) gemm_stage<AI, BI>(A + (kt + 1) * 64, lda, B + (kt + 1) * 64, ldb, lds + ((kt + 1) & 1) * 32768, tid);
; #pragma unroll
;     for (int ks = 0; ks < 4; ++ks) {
;       const int co = ((ks * 2 + h) ^ sw) << 4;
;       s16x8 fa[AI], fb[BI];
; #pragma unroll
;       for (int i = 0; i < AI; ++i) fa[i] = *(const s16x8*)(cur + offA + i * 4096 + co);
; #pragma unroll
;       for (int i = 0; i < BI; ++i) fb[i] = *(const s16x8*)(cur + offB + i * 4096 + co);
; #pragma unroll
;       for (int i = 0; i < AI; ++i)
; #pragma unroll
;         for (int j = 0; j < BI; ++j) acc[i][j] = MFMA(fa[i], fb[j], acc[i][j]);
;     }
;     asm volatile("s_waitcnt vmcnt(0)" ::: "memory");
;     __syncthreads();
;   }
.Lgc1_kloop:
	s_waitcnt vmcnt(9)
	s_barrier
	s_add_u32 m0, s17, 49152
	s_nop 0
	global_load_lds_dwordx4 v62, s[8:9]
	s_add_u32 m0, s17, 53248
	s_nop 0
	global_load_lds_dwordx4 v62, s[28:29]
	s_add_u32 m0, s17, 57344
	s_nop 0
	global_load_lds_dwordx4 v63, s[28:29]
	s_add_u32 s8, s8, 64
	s_addc_u32 s9, s9, 0
	s_add_u32 s28, s28, 64
	s_addc_u32 s29, s29, 0
	ds_read_b128 v[34:37], v58 offset:0
	ds_read_b128 v[42:45], v60 offset:0
	ds_read_b128 v[46:49], v60 offset:2048
	ds_read_b128 v[38:41], v59 offset:0
	ds_read_b128 v[50:53], v61 offset:0
	ds_read_b128 v[54:57], v61 offset:2048
	s_waitcnt lgkmcnt(4)
	v_mfma_f32_32x32x16_bf16 v[2:17], v[34:37], v[42:45], v[2:17]
	s_waitcnt lgkmcnt(3)
	v_mfma_f32_32x32x16_bf16 v[18:33], v[34:37], v[46:49], v[18:33]
	s_waitcnt lgkmcnt(1)
	v_mfma_f32_32x32x16_bf16 v[2:17], v[38:41], v[50:53], v[2:17]
	s_waitcnt lgkmcnt(0)
	v_mfma_f32_32x32x16_bf16 v[18:33], v[38:41], v[54:57], v[18:33]
	s_waitcnt vmcnt(9)
	s_barrier
	s_add_u32 m0, s17, 0
	s_nop 0
	global_load_lds_dwordx4 v62, s[8:9]
	s_add_u32 m0, s17, 4096
	s_nop 0
	global_load_lds_dwordx4 v62, s[28:29]
	s_add_u32 m0, s17, 8192
	s_nop 0
	global_load_lds_dwordx4 v63, s[28:29]
	s_add_u32 s8, s8, 64
	s_addc_u32 s9, s9, 0
	s_add_u32 s28, s28, 64
	s_addc_u32 s29, s29, 0
	ds_read_b128 v[34:37], v58 offset:12288
	ds_read_b128 v[42:45], v60 offset:12288
	ds_read_b128 v[46:49], v60 offset:14336
	ds_read_b128 v[38:41], v59 offset:12288
	ds_read_b128 v[50:53], v61 offset:12288
	ds_read_b128 v[54:57], v61 offset:14336
	s_waitcnt lgkmcnt(4)
	v_mfma_f32_32x32x16_bf16 v[2:17], v[34:37], v[42:45], v[2:17]
	s_waitcnt lgkmcnt(3)
	v_mfma_f32_32x32x16_bf16 v[18:33], v[34:37], v[46:49], v[18:33]
	s_waitcnt lgkmcnt(1)
	v_mfma_f32_32x32x16_bf16 v[2:17], v[38:41], v[50:53], v[2:17]
	s_waitcnt lgkmcnt(0)
	v_mfma_f32_32x32x16_bf16 v[18:33], v[38:41], v[54:57], v[18:33]
	s_waitcnt vmcnt(9)
	s_barrier
	s_add_u32 m0, s17, 12288
	s_nop 0
	global_load_lds_dwordx4 v62, s[8:9]
	s_add_u32 m0, s17, 16384
	s_nop 0
	global_load_lds_dwordx4 v62, s[28:29]
	s_add_u32 m0, s17, 20480
	s_nop 0
	global_load_lds_dwordx4 v63, s[28:29]
	s_add_u32 s8, s8, 64
	s_addc_u32 s9, s9, 0
	s_add_u32 s28, s28, 64
	s_addc_u32 s29, s29, 0
	ds_read_b128 v[34:37], v58 offset:24576
	ds_read_b128 v[42:45], v60 offset:24576
	ds_read_b128 v[46:49], v60 offset:26624
	ds_read_b128 v[38:41], v59 offset:24576
	ds_read_b128 v[50:53], v61 offset:24576
	ds_read_b128 v[54:57], v61 offset:26624
	s_waitcnt lgkmcnt(4)
	v_mfma_f32_32x32x16_bf16 v[2:17], v[34:37], v[42:45], v[2:17]
	s_waitcnt lgkmcnt(3)
	v_mfma_f32_32x32x16_bf16 v[18:33], v[34:37], v[46:49], v[18:33]
	s_waitcnt lgkmcnt(1)
	v_mfma_f32_32x32x16_bf16 v[2:17], v[38:41], v[50:53], v[2:17]
	s_waitcnt lgkmcnt(0)
	v_mfma_f32_32x32x16_bf16 v[18:33], v[38:41], v[54:57], v[18:33]
	s_waitcnt vmcnt(9)
	s_barrier
	s_add_u32 m0, s17, 24576
	s_nop 0
	global_load_lds_dwordx4 v62, s[8:9]
	s_add_u32 m0, s17, 28672
	s_nop 0
	global_load_lds_dwordx4 v62, s[28:29]
	s_add_u32 m0, s17, 32768
	s_nop 0
	global_load_lds_dwordx4 v63, s[28:29]
	s_add_u32 s8, s8, 64
	s_addc_u32 s9, s9, 0
	s_add_u32 s28, s28, 64
	s_addc_u32 s29, s29, 0
	ds_read_b128 v[34:37], v58 offset:36864
	ds_read_b128 v[42:45], v60 offset:36864
	ds_read_b128 v[46:49], v60 offset:38912
	ds_read_b128 v[38:41], v59 offset:36864
	ds_read_b128 v[50:53], v61 offset:36864
	ds_read_b128 v[54:57], v61 offset:38912
	s_waitcnt lgkmcnt(4)
	v_mfma_f32_32x32x16_bf16 v[2:17], v[34:37], v[42:45], v[2:17]
	s_waitcnt lgkmcnt(3)
	v_mfma_f32_32x32x16_bf16 v[18:33], v[34:37], v[46:49], v[18:33]
	s_waitcnt lgkmcnt(1)
	v_mfma_f32_32x32x16_bf16 v[2:17], v[38:41], v[50:53], v[2:17]
	s_waitcnt lgkmcnt(0)
	v_mfma_f32_32x32x16_bf16 v[18:33], v[38:41], v[54:57], v[18:33]
	s_waitcnt vmcnt(9)
	s_barrier
	s_add_u32 m0, s17, 36864
	s_nop 0
	global_load_lds_dwordx4 v62, s[8:9]
	s_add_u32 m0, s17, 40960
	s_nop 0
	global_load_lds_dwordx4 v62, s[28:29]
	s_add_u32 m0, s17, 45056
	s_nop 0
	global_load_lds_dwordx4 v63, s[28:29]
	s_add_u32 s8, s8, 64
	s_addc_u32 s9, s9, 0
	s_add_u32 s28, s28, 64
	s_addc_u32 s29, s29, 0
	ds_read_b128 v[34:37], v58 offset:49152
	ds_read_b128 v[42:45], v60 offset:49152
	ds_read_b128 v[46:49], v60 offset:51200
	ds_read_b128 v[38:41], v59 offset:49152
	ds_read_b128 v[50:53], v61 offset:49152
	ds_read_b128 v[54:57], v61 offset:51200
	s_waitcnt lgkmcnt(4)
	v_mfma_f32_32x32x16_bf16 v[2:17], v[34:37], v[42:45], v[2:17]
	s_waitcnt lgkmcnt(3)
	v_mfma_f32_32x32x16_bf16 v[18:33], v[34:37], v[46:49], v[18:33]
	s_waitcnt lgkmcnt(1)
	v_mfma_f32_32x32x16_bf16 v[2:17], v[38:41], v[50:53], v[2:17]
	s_waitcnt lgkmcnt(0)
	v_mfma_f32_32x32x16_bf16 v[18:33], v[38:41], v[54:57], v[18:33]
	s_sub_u32 s18, s18, 1
	s_cmp_lg_u32 s18, 0
	s_cbranch_scc1 .Lgc1_kloop
	s_waitcnt vmcnt(9)
	s_barrier
	s_add_u32 m0, s17, 49152
	s_nop 0
	global_load_lds_dwordx4 v62, s[8:9]
	s_add_u32 m0, s17, 53248
	s_nop 0
	global_load_lds_dwordx4 v62, s[28:29]
	s_add_u32 m0, s17, 57344
	s_nop 0
	global_load_lds_dwordx4 v63, s[28:29]
	s_add_u32 s8, s8, 64
	s_addc_u32 s9, s9, 0
	s_add_u32 s28, s28, 64
	s_addc_u32 s29, s29, 0
	ds_read_b128 v[34:37], v58 offset:0
	ds_read_b128 v[42:45], v60 offset:0
	ds_read_b128 v[46:49], v60 offset:2048
	ds_read_b128 v[38:41], v59 offset:0
	ds_read_b128 v[50:53], v61 offset:0
	ds_read_b128 v[54:57], v61 offset:2048
	s_waitcnt lgkmcnt(4)
	v_mfma_f32_32x32x16_bf16 v[2:17], v[34:37], v[42:45], v[2:17]
	s_waitcnt lgkmcnt(3)
	v_mfma_f32_32x32x16_bf16 v[18:33], v[34:37], v[46:49], v[18:33]
	s_waitcnt lgkmcnt(1)
	v_mfma_f32_32x32x16_bf16 v[2:17], v[38:41], v[50:53], v[2:17]
	s_waitcnt lgkmcnt(0)
	v_mfma_f32_32x32x16_bf16 v[18:33], v[38:41], v[54:57], v[18:33]
	s_waitcnt vmcnt(9)
	s_barrier
; #define MFMA(a, b, c) __builtin_amdgcn_mfma_f32_32x32x16_bf16((a), (b), (c), 0, 0, 0)
; template <int AI, int BI>
; DI void gemm_tile(const u16* __restrict__ A, int lda, const u16* __restrict__ B, int ldb, int nk, bool swap,
;                   f32x16 (&acc)[AI][BI], char* lds) {
;     ...
;   for (int kt = 0; kt < nk; ++kt) {
;     const char* cur = lds + (kt & 1) * 32768;
;     if (kt + 1 < nk) gemm_stage<AI, BI>(A + (kt + 1) * 64, lda, B + (kt + 1) * 64, ldb, lds + ((kt + 1) & 1) * 32768, tid);
; #pragma unroll
;     for (int ks = 0; ks < 4; ++ks) {
;       const int co = ((ks * 2 + h) ^ sw) << 4;
;       s16x8 fa[AI], fb[BI];
; #pragma unroll
;       for (int i = 0; i < AI; ++i) fa[i] = *(const s16x8*)(cur + offA + i * 4096 + co);
; #pragma unroll
;       for (int i = 0; i < BI; ++i) fb[i] = *(const s16x8*)(cur + offB + i * 4096 + co);
; #pragma unroll
;       for (int i = 0; i < AI; ++i)
; #pragma unroll
;         for (int j = 0; j < BI; ++j) acc[i][j] = MFMA(fa[i], fb[j], acc[i][j]);
;     }
;     asm volatile("s_waitcnt vmcnt(0)" ::: "memory");
;     __syncthreads();
;   }
	s_add_u32 m0, s17, 0
	s_nop 0
	global_load_lds_dwordx4 v62, s[8:9]
	s_add_u32 m0, s17, 4096
	s_nop 0
	global_load_lds_dwordx4 v62, s[28:29]
	s_add_u32 m0, s17, 8192
	s_nop 0
	global_load_lds_dwordx4 v63, s[28:29]
	s_add_u32 s8, s8, 64
	s_addc_u32 s9, s9, 0
	s_add_u32 s28, s28, 64
	s_addc_u32 s29, s29, 0
	ds_read_b128 v[34:37], v58 offset:12288
	ds_read_b128 v[42:45], v60 offset:12288
	ds_read_b128 v[46:49], v60 offset:14336
	ds_read_b128 v[38:41], v59 offset:12288
	ds_read_b128 v[50:53], v61 offset:12288
	ds_read_b128 v[54:57], v61 offset:14336
	s_waitcnt lgkmcnt(4)
	v_mfma_f32_32x32x16_bf16 v[2:17], v[34:37], v[42:45], v[2:17]
	s_waitcnt lgkmcnt(3)
	v_mfma_f32_32x32x16_bf16 v[18:33], v[34:37], v[46:49], v[18:33]
	s_waitcnt lgkmcnt(1)
	v_mfma_f32_32x32x16_bf16 v[2:17], v[38:41], v[50:53], v[2:17]
	s_waitcnt lgkmcnt(0)
	v_mfma_f32_32x32x16_bf16 v[18:33], v[38:41], v[54:57], v[18:33]
	s_waitcnt vmcnt(9)
	s_barrier
	s_add_u32 m0, s17, 12288
	s_nop 0
	global_load_lds_dwordx4 v62, s[8:9]
	s_add_u32 m0, s17, 16384
	s_nop 0
	global_load_lds_dwordx4 v62, s[28:29]
	s_add_u32 m0, s17, 20480
	s_nop 0
	global_load_lds_dwordx4 v63, s[28:29]
	s_add_u32 s8, s8, 64
	s_addc_u32 s9, s9, 0
	s_add_u32 s28, s28, 64
	s_addc_u32 s29, s29, 0
	ds_read_b128 v[34:37], v58 offset:24576
	ds_read_b128 v[42:45], v60 offset:24576
	ds_read_b128 v[46:49], v60 offset:26624
	ds_read_b128 v[38:41], v59 offset:24576
	ds_read_b128 v[50:53], v61 offset:24576
	ds_read_b128 v[54:57], v61 offset:26624
	s_waitcnt lgkmcnt(4)
	v_mfma_f32_32x32x16_bf16 v[2:17], v[34:37], v[42:45], v[2:17]
	s_waitcnt lgkmcnt(3)
	v_mfma_f32_32x32x16_bf16 v[18:33], v[34:37], v[46:49], v[18:33]
	s_waitcnt lgkmcnt(1)
	v_mfma_f32_32x32x16_bf16 v[2:17], v[38:41], v[50:53], v[2:17]
	s_waitcnt lgkmcnt(0)
	v_mfma_f32_32x32x16_bf16 v[18:33], v[38:41], v[54:57], v[18:33]
	s_waitcnt vmcnt(9)
	s_barrier
	ds_read_b128 v[34:37], v58 offset:36864
	ds_read_b128 v[42:45], v60 offset:36864
	ds_read_b128 v[46:49], v60 offset:38912
	ds_read_b128 v[38:41], v59 offset:36864
	ds_read_b128 v[50:53], v61 offset:36864
	ds_read_b128 v[54:57], v61 offset:38912
	s_waitcnt lgkmcnt(4)
	v_mfma_f32_32x32x16_bf16 v[2:17], v[34:37], v[42:45], v[2:17]
	s_waitcnt lgkmcnt(3)
	v_mfma_f32_32x32x16_bf16 v[18:33], v[34:37], v[46:49], v[18:33]
	s_waitcnt lgkmcnt(1)
	v_mfma_f32_32x32x16_bf16 v[2:17], v[38:41], v[50:53], v[2:17]
	s_waitcnt lgkmcnt(0)
	v_mfma_f32_32x32x16_bf16 v[18:33], v[38:41], v[54:57], v[18:33]
	s_waitcnt vmcnt(6)
	s_barrier
	ds_read_b128 v[34:37], v58 offset:49152
	ds_read_b128 v[42:45], v60 offset:49152
	ds_read_b128 v[46:49], v60 offset:51200
	ds_read_b128 v[38:41], v59 offset:49152
	ds_read_b128 v[50:53], v61 offset:49152
	ds_read_b128 v[54:57], v61 offset:51200
	s_waitcnt lgkmcnt(4)
	v_mfma_f32_32x32x16_bf16 v[2:17], v[34:37], v[42:45], v[2:17]
	s_waitcnt lgkmcnt(3)
	v_mfma_f32_32x32x16_bf16 v[18:33], v[34:37], v[46:49], v[18:33]
	s_waitcnt lgkmcnt(1)
	v_mfma_f32_32x32x16_bf16 v[2:17], v[38:41], v[50:53], v[2:17]
	s_waitcnt lgkmcnt(0)
	v_mfma_f32_32x32x16_bf16 v[18:33], v[38:41], v[54:57], v[18:33]
	s_waitcnt vmcnt(3)
	s_barrier
	ds_read_b128 v[34:37], v58 offset:0
	ds_read_b128 v[42:45], v60 offset:0
	ds_read_b128 v[46:49], v60 offset:2048
	ds_read_b128 v[38:41], v59 offset:0
	ds_read_b128 v[50:53], v61 offset:0
	ds_read_b128 v[54:57], v61 offset:2048
	s_waitcnt lgkmcnt(4)
	v_mfma_f32_32x32x16_bf16 v[2:17], v[34:37], v[42:45], v[2:17]
	s_waitcnt lgkmcnt(3)
	v_mfma_f32_32x32x16_bf16 v[18:33], v[34:37], v[46:49], v[18:33]
	s_waitcnt lgkmcnt(1)
	v_mfma_f32_32x32x16_bf16 v[2:17], v[38:41], v[50:53], v[2:17]
	s_waitcnt lgkmcnt(0)
	v_mfma_f32_32x32x16_bf16 v[18:33], v[38:41], v[54:57], v[18:33]
	s_waitcnt vmcnt(0)
	s_barrier
	ds_read_b128 v[34:37], v58 offset:12288
	ds_read_b128 v[42:45], v60 offset:12288
	ds_read_b128 v[46:49], v60 offset:14336
	ds_read_b128 v[38:41], v59 offset:12288
	ds_read_b128 v[50:53], v61 offset:12288
	ds_read_b128 v[54:57], v61 offset:14336
	s_waitcnt lgkmcnt(4)
	v_mfma_f32_32x32x16_bf16 v[2:17], v[34:37], v[42:45], v[2:17]
	s_waitcnt lgkmcnt(3)
	v_mfma_f32_32x32x16_bf16 v[18:33], v[34:37], v[46:49], v[18:33]
	s_waitcnt lgkmcnt(1)
	v_mfma_f32_32x32x16_bf16 v[2:17], v[38:41], v[50:53], v[2:17]
	s_waitcnt lgkmcnt(0)
; #define GAS __attribute__((address_space(1)))
; DI int opaque0() { int z = 0; asm volatile("" : "+v"(z)); return z; }
; template <int AI>
; DI void gu_tile(char* wsb, int sub, int m0, int n0, char* lds) {
;     ...
;   const int m0e = m0 + opaque0();
;   const int hc = (n0 >> 1) + wb * 32 + r;
;   GAS u16* HIDu = uptr(HID);
;   const unsigned ib = (unsigned)((m0e + wa * 32 * AI + 4 * h) * 2816 + hc);
; #pragma unroll
;   for (int ai = 0; ai < AI; ++ai)
; #pragma unroll
;     for (int reg = 0; reg < 16; ++reg) {
;       float g = acc[ai][0][reg], u = acc[ai][1][reg];
;       float v = g * __builtin_amdgcn_rcpf(1.f + __expf(-g)) * u;
;       HIDu[ib + (unsigned)((ai * 32 + (reg & 3) + 8 * (reg >> 2)) * 2816)] = f2bf(v);
;       if ((reg & 7) == 7) __builtin_amdgcn_sched_barrier(0);
;     }
	v_mfma_f32_32x32x16_bf16 v[18:33], v[38:41], v[54:57], v[18:33]
	s_nop 7
	s_nop 7
	v_mul_f32_e32 v66, 0xbfb8aa3b, v2
	v_mul_f32_e32 v68, 0xbfb8aa3b, v3
	v_exp_f32_e32 v66, v66
	v_exp_f32_e32 v68, v68
	v_add_u32_e32 v67, 0x0, v64
	v_add_f32_e32 v66, 1.0, v66
	v_add_f32_e32 v68, 1.0, v68
	v_rcp_f32_e32 v66, v66
	v_rcp_f32_e32 v68, v68
	v_add_u32_e32 v69, 0x1600, v64
	v_mul_f32_e32 v66, v2, v66
	v_mul_f32_e32 v68, v3, v68
	v_mul_f32_e32 v66, v18, v66
	v_mul_f32_e32 v68, v19, v68
	v_cvt_pk_bf16_f32 v66, v66, v66
	v_cvt_pk_bf16_f32 v68, v68, v68
	global_store_short v67, v66, s[34:35]
	global_store_short v69, v68, s[34:35]
	v_mul_f32_e32 v66, 0xbfb8aa3b, v4
	v_mul_f32_e32 v68, 0xbfb8aa3b, v5
	v_exp_f32_e32 v66, v66
	v_exp_f32_e32 v68, v68
	v_add_u32_e32 v67, 0x2c00, v64
	v_add_f32_e32 v66, 1.0, v66
	v_add_f32_e32 v68, 1.0, v68
	v_rcp_f32_e32 v66, v66
	v_rcp_f32_e32 v68, v68
	v_add_u32_e32 v69, 0x4200, v64
	v_mul_f32_e32 v66, v4, v66
	v_mul_f32_e32 v68, v5, v68
	v_mul_f32_e32 v66, v20, v66
	v_mul_f32_e32 v68, v21, v68
	v_cvt_pk_bf16_f32 v66, v66, v66
	v_cvt_pk_bf16_f32 v68, v68, v68
	global_store_short v67, v66, s[34:35]
	global_store_short v69, v68, s[34:35]
	v_mul_f32_e32 v66, 0xbfb8aa3b, v6
	v_mul_f32_e32 v68, 0xbfb8aa3b, v7
	v_exp_f32_e32 v66, v66
	v_exp_f32_e32 v68, v68
	v_add_u32_e32 v67, 0xb000, v64
	v_add_f32_e32 v66, 1.0, v66
	v_add_f32_e32 v68, 1.0, v68
	v_rcp_f32_e32 v66, v66
	v_rcp_f32_e32 v68, v68
	v_add_u32_e32 v69, 0xc600, v64
	v_mul_f32_e32 v66, v6, v66
	v_mul_f32_e32 v68, v7, v68
	v_mul_f32_e32 v66, v22, v66
	v_mul_f32_e32 v68, v23, v68
	v_cvt_pk_bf16_f32 v66, v66, v66
	v_cvt_pk_bf16_f32 v68, v68, v68
	global_store_short v67, v66, s[34:35]
	global_store_short v69, v68, s[34:35]
	v_mul_f32_e32 v66, 0xbfb8aa3b, v8
	v_mul_f32_e32 v68, 0xbfb8aa3b, v9
	v_exp_f32_e32 v66, v66
	v_exp_f32_e32 v68, v68
	v_add_u32_e32 v67, 0xdc00, v64
	v_add_f32_e32 v66, 1.0, v66
	v_add_f32_e32 v68, 1.0, v68
	v_rcp_f32_e32 v66, v66
	v_rcp_f32_e32 v68, v68
	v_add_u32_e32 v69, 0xf200, v64
	v_mul_f32_e32 v66, v8, v66
	v_mul_f32_e32 v68, v9, v68
	v_mul_f32_e32 v66, v24, v66
	v_mul_f32_e32 v68, v25, v68
	v_cvt_pk_bf16_f32 v66, v66, v66
	v_cvt_pk_bf16_f32 v68, v68, v68
	global_store_short v67, v66, s[34:35]
	global_store_short v69, v68, s[34:35]
	v_mul_f32_e32 v66, 0xbfb8aa3b, v10
	v_mul_f32_e32 v68, 0xbfb8aa3b, v11
	v_exp_f32_e32 v66, v66
	v_exp_f32_e32 v68, v68
	v_add_u32_e32 v67, 0x16000, v64
	v_add_f32_e32 v66, 1.0, v66
	v_add_f32_e32 v68, 1.0, v68
	v_rcp_f32_e32 v66, v66
	v_rcp_f32_e32 v68, v68
	v_add_u32_e32 v69, 0x17600, v64
	v_mul_f32_e32 v66, v10, v66
	v_mul_f32_e32 v68, v11, v68
	v_mul_f32_e32 v66, v26, v66
	v_mul_f32_e32 v68, v27, v68
	v_cvt_pk_bf16_f32 v66, v66, v66
	v_cvt_pk_bf16_f32 v68, v68, v68
	global_store_short v67, v66, s[34:35]
	global_store_short v69, v68, s[34:35]
	v_mul_f32_e32 v66, 0xbfb8aa3b, v12
	v_mul_f32_e32 v68, 0xbfb8aa3b, v13
	v_exp_f32_e32 v66, v66
	v_exp_f32_e32 v68, v68
	v_add_u32_e32 v67, 0x18c00, v64
	v_add_f32_e32 v66, 1.0, v66
	v_add_f32_e32 v68, 1.0, v68
	v_rcp_f32_e32 v66, v66
	v_rcp_f32_e32 v68, v68
	v_add_u32_e32 v69, 0x1a200, v64
	v_mul_f32_e32 v66, v12, v66
	v_mul_f32_e32 v68, v13, v68
	v_mul_f32_e32 v66, v28, v66
	v_mul_f32_e32 v68, v29, v68
	v_cvt_pk_bf16_f32 v66, v66, v66
	v_cvt_pk_bf16_f32 v68, v68, v68
	global_store_short v67, v66, s[34:35]
	global_store_short v69, v68, s[34:35]
	v_mul_f32_e32 v66, 0xbfb8aa3b, v14
	v_mul_f32_e32 v68, 0xbfb8aa3b, v15
	v_exp_f32_e32 v66, v66
	v_exp_f32_e32 v68, v68
	v_add_u32_e32 v67, 0x21000, v64
	v_add_f32_e32 v66, 1.0, v66
	v_add_f32_e32 v68, 1.0, v68
	v_rcp_f32_e32 v66, v66
	v_rcp_f32_e32 v68, v68
	v_add_u32_e32 v69, 0x22600, v64
	v_mul_f32_e32 v66, v14, v66
	v_mul_f32_e32 v68, v15, v68
	v_mul_f32_e32 v66, v30, v66
	v_mul_f32_e32 v68, v31, v68
	v_cvt_pk_bf16_f32 v66, v66, v66
	v_cvt_pk_bf16_f32 v68, v68, v68
	global_store_short v67, v66, s[34:35]
	global_store_short v69, v68, s[34:35]
	v_mul_f32_e32 v66, 0xbfb8aa3b, v16
	v_mul_f32_e32 v68, 0xbfb8aa3b, v17
	v_exp_f32_e32 v66, v66
	v_exp_f32_e32 v68, v68
	v_add_u32_e32 v67, 0x23c00, v64
	v_add_f32_e32 v66, 1.0, v66
	v_add_f32_e32 v68, 1.0, v68
	v_rcp_f32_e32 v66, v66
	v_rcp_f32_e32 v68, v68
	v_add_u32_e32 v69, 0x25200, v64
	v_mul_f32_e32 v66, v16, v66
	v_mul_f32_e32 v68, v17, v68
	v_mul_f32_e32 v66, v32, v66
	v_mul_f32_e32 v68, v33, v68
	v_cvt_pk_bf16_f32 v66, v66, v66
	v_cvt_pk_bf16_f32 v68, v68, v68
	global_store_short v67, v66, s[34:35]
	global_store_short v69, v68, s[34:35]
	s_add_u32 s36, s36, 0x200
	s_cmpk_lt_u32 s36, 0x580
	s_cbranch_scc1 .Lgc1_tile
	s_branch .Lgc1_exit
; #define MFMA(a, b, c) __builtin_amdgcn_mfma_f32_32x32x16_bf16((a), (b), (c), 0, 0, 0)
; #define TIDX opaque_tid()
; template <int AI, int BI>
; DI void gemm_tile(const u16* __restrict__ A, int lda, const u16* __restrict__ B, int ldb, int nk, bool swap,
;                   f32x16 (&acc)[AI][BI], char* lds) {
;   const int tid = TIDX, lane = tid & 63, wid = tid >> 6;
;   gemm_stage<AI, BI>(A, lda, B, ldb, lds, tid);
;   asm volatile("s_waitcnt vmcnt(0)" ::: "memory");
;   __syncthreads();
;   const int wa = wid >> 1, wb = wid & 1, r = lane & 31, h = lane >> 5, sw = (r >> 1) & 7;
;   const int offA = (swap ? 16384 : 0) + (wa * 32 * AI + r) * 128;
;   const int offB = (swap ? 0 : 16384) + (wb * 32 * BI + r) * 128;
;   for (int kt = 0; kt < nk; ++kt) {
;     const char* cur = lds + (kt & 1) * 32768;
;     if (kt + 1 < nk) gemm_stage<AI, BI>(A + (kt + 1) * 64, lda, B + (kt + 1) * 64, ldb, lds + ((kt + 1) & 1) * 32768, tid);
; #pragma unroll
;     for (int ks = 0; ks < 4; ++ks) {
;       const int co = ((ks * 2 + h) ^ sw) << 4;
;       s16x8 fa[AI], fb[BI];
; #pragma unroll
;       for (int i = 0; i < AI; ++i) fa[i] = *(const s16x8*)(cur + offA + i * 4096 + co);
; #pragma unroll
;       for (int i = 0; i < BI; ++i) fb[i] = *(const s16x8*)(cur + offB + i * 4096 + co);
; #pragma unroll
;       for (int i = 0; i < AI; ++i)
; #pragma unroll
;         for (int j = 0; j < BI; ++j) acc[i][j] = MFMA(fa[i], fb[j], acc[i][j]);
;     }
;     asm volatile("s_waitcnt vmcnt(0)" ::: "memory");
;     __syncthreads();
;   }
; DI bool next_tile(int rnd, int MT, int NT, int& mt, int& nt) {
;   const int G8 = gridDim.x >> 3, x = blockIdx.x & 7, slot = blockIdx.x >> 3;
;   const int T = (rnd * 8 + x) * G8 + slot;
;   if (T >= MT * NT) return false;
;   const int band = T / (NT * 8), rem = T - band * NT * 8;
;   nt = rem >> 3; mt = band * 8 + (rem & 7);
.LBB0_423:
	s_and_b32 s8, s14, 0xffff
	s_mul_hi_u32 s9, s8, 0xba2e8c
	s_mul_i32 s8, s8, 0xba2f
	s_lshr_b32 s8, s8, 24
	s_lshl_b32 s8, s8, 9
	s_and_b32 s17, s16, 0x1c0
	s_mulk_i32 s9, 0x1600
	s_or_b32 s17, s8, s17
	s_sub_i32 s9, s15, s9
	s_addk_i32 s17, 0x4000
	s_and_b32 s8, s9, 0xffffff80
	v_mov_b32_e32 v46, v178
	v_mov_b32_e32 v47, v178
	s_lshl_b32 s9, s17, 11
	v_mov_b32_e32 v8, v178
	s_add_u32 s28, s10, s9
	s_addc_u32 s29, s11, 0
	v_lshrrev_b32_e32 v0, 4, v8
	s_ashr_i32 s9, s8, 31
	v_xor_b32_e32 v0, v0, v8
	v_add_u32_e32 v9, 0x100, v8
	s_lshl_b64 s[34:35], s[8:9], 11
	v_lshlrev_b32_e32 v0, 4, v0
	v_ashrrev_i32_e32 v4, 3, v8
	v_ashrrev_i32_e32 v6, 3, v9
	s_add_u32 s34, s12, s34
	v_and_b32_e32 v0, 0x70, v0
	v_ashrrev_i32_e32 v5, 31, v4
	v_ashrrev_i32_e32 v7, 31, v6
	s_addc_u32 s35, s13, s35
	v_lshl_add_u64 v[2:3], s[28:29], 0, v[0:1]
	v_lshlrev_b64 v[4:5], 11, v[4:5]
	v_lshlrev_b64 v[6:7], 11, v[6:7]
	v_lshl_add_u64 v[34:35], v[2:3], 0, v[4:5]
	v_lshl_add_u64 v[36:37], v[2:3], 0, v[6:7]
	v_lshl_add_u64 v[2:3], s[34:35], 0, v[0:1]
	v_add_u32_e32 v0, 0x200, v8
	v_lshl_add_u64 v[40:41], v[2:3], 0, v[4:5]
	v_ashrrev_i32_e32 v4, 3, v0
	v_ashrrev_i32_e32 v5, 31, v4
	v_lshl_add_u64 v[38:39], v[2:3], 0, v[6:7]
	v_lshlrev_b64 v[4:5], 11, v[4:5]
	v_add_u32_e32 v6, 0x300, v8
	v_lshl_add_u64 v[42:43], v[2:3], 0, v[4:5]
	v_ashrrev_i32_e32 v4, 3, v6
	v_ashrrev_i32_e32 v5, 31, v4
	v_lshlrev_b32_e32 v55, 4, v8
	v_lshlrev_b64 v[4:5], 11, v[4:5]
	v_readfirstlane_b32 s9, v55
	v_lshlrev_b32_e32 v56, 4, v9
	v_lshl_add_u64 v[44:45], v[2:3], 0, v[4:5]
	v_and_b32_e32 v2, 31, v8
	v_lshrrev_b32_e32 v7, 2, v8
	s_mov_b32 m0, s9
	v_readfirstlane_b32 s18, v56
	v_add_u32_e32 v57, 0x4000, v55
	v_and_or_b32 v2, v7, s49, v2
	global_load_lds_dwordx4 v[34:35], off
	s_mov_b32 m0, s18
	v_readfirstlane_b32 s28, v57
	v_add_u32_e32 v58, 0x4000, v56
	v_lshlrev_b32_e32 v0, 4, v0
	v_lshlrev_b32_e32 v4, 4, v6
	v_lshrrev_b32_e32 v3, 5, v8
	v_bfe_u32 v6, v8, 1, 3
	v_lshlrev_b32_e32 v53, 7, v2
	v_lshlrev_b32_e32 v2, 7, v8
	global_load_lds_dwordx4 v[36:37], off
	s_mov_b32 m0, s28
	v_readfirstlane_b32 s29, v58
	v_add_u32_e32 v65, 0x4000, v0
	v_bfe_u32 v5, v8, 5, 1
	v_and_b32_e32 v67, 0x2f80, v2
	v_bitop3_b32 v2, v3, v6, 1 bitop3:0x6c
	global_load_lds_dwordx4 v[40:41], off
	s_mov_b32 m0, s29
	v_readfirstlane_b32 s34, v65
	v_add_u32_e32 v66, 0x4000, v4
	v_lshlrev_b32_e32 v7, 4, v2
	v_bitop3_b32 v2, v5, v6, 2 bitop3:0x36
	global_load_lds_dwordx4 v[38:39], off
	s_mov_b32 m0, s34
	v_readfirstlane_b32 s41, v66
	v_lshlrev_b32_e32 v49, 4, v2
	v_bitop3_b32 v2, v5, v6, 4 bitop3:0x36
	v_add_u32_e32 v63, 0x8000, v55
	global_load_lds_dwordx4 v[42:43], off
	s_mov_b32 m0, s41
	v_lshlrev_b32_e32 v51, 4, v2
	v_bitop3_b32 v2, v5, v6, 6 bitop3:0x36
	v_readfirstlane_b32 s35, v63
	v_add_u32_e32 v60, 0x8000, v56
	global_load_lds_dwordx4 v[44:45], off
	s_waitcnt vmcnt(0)
	v_lshlrev_b32_e32 v80, 4, v2
	v_lshl_add_u64 v[2:3], v[34:35], 0, s[52:53]
	s_mov_b32 m0, s35
	v_readfirstlane_b32 s36, v60
	v_add_u32_e32 v59, 0xc000, v55
	s_waitcnt vmcnt(0)
	s_waitcnt vmcnt(0) lgkmcnt(0)
	s_barrier
	global_load_lds_dwordx4 v[2:3], off
	v_lshl_add_u64 v[2:3], v[36:37], 0, s[52:53]
	s_mov_b32 m0, s36
	v_readfirstlane_b32 s37, v59
	v_add_u32_e32 v61, 0xc000, v56
	global_load_lds_dwordx4 v[2:3], off
	v_lshl_add_u64 v[2:3], v[40:41], 0, s[52:53]
	s_mov_b32 m0, s37
	v_readfirstlane_b32 s40, v61
	v_add_u32_e32 v62, 0xc000, v0
	global_load_lds_dwordx4 v[2:3], off
	v_lshl_add_u64 v[2:3], v[38:39], 0, s[52:53]
	s_mov_b32 m0, s40
	v_readfirstlane_b32 s46, v62
	v_add_u32_e32 v64, 0xc000, v4
	global_load_lds_dwordx4 v[2:3], off
	v_lshl_add_u64 v[2:3], v[42:43], 0, s[52:53]
	s_mov_b32 m0, s46
	v_readfirstlane_b32 s47, v64
	global_load_lds_dwordx4 v[2:3], off
	v_lshl_add_u64 v[2:3], v[44:45], 0, s[52:53]
	s_mov_b32 m0, s47
	v_or_b32_e32 v0, v53, v7
	global_load_lds_dwordx4 v[2:3], off
	ds_read_b128 v[18:21], v0
	v_or_b32_e32 v50, v67, v7
	ds_read_b128 v[2:5], v50 offset:16384
	ds_read_b128 v[22:25], v50 offset:20480
	v_or_b32_e32 v48, v53, v49
	ds_read_b128 v[68:71], v48
	s_waitcnt lgkmcnt(0)
	v_mfma_f32_32x32x16_bf16 v[2:17], v[18:21], v[2:5], 0
	v_or_b32_e32 v49, v67, v49
	ds_read_b128 v[72:75], v49 offset:16384
	ds_read_b128 v[76:79], v49 offset:20480
	v_or_b32_e32 v52, v53, v51
	v_or_b32_e32 v51, v67, v51
	v_or_b32_e32 v54, v53, v80
	v_or_b32_e32 v53, v67, v80
	s_mov_b32 m0, s9
	v_mfma_f32_32x32x16_bf16 v[18:33], v[18:21], v[22:25], 0
	s_ashr_i32 s8, s8, 1
	s_waitcnt lgkmcnt(1)
	v_mfma_f32_32x32x16_bf16 v[2:17], v[68:71], v[72:75], v[2:17]
	s_waitcnt lgkmcnt(0)
	v_mfma_f32_32x32x16_bf16 v[18:33], v[68:71], v[76:79], v[18:33]
	ds_read_b128 v[68:71], v52
	ds_read_b128 v[72:75], v51 offset:16384
	ds_read_b128 v[76:79], v51 offset:20480
	s_waitcnt lgkmcnt(1)
	v_mfma_f32_32x32x16_bf16 v[2:17], v[68:71], v[72:75], v[2:17]
	s_waitcnt lgkmcnt(0)
	v_mfma_f32_32x32x16_bf16 v[18:33], v[68:71], v[76:79], v[18:33]
	ds_read_b128 v[68:71], v54
	ds_read_b128 v[72:75], v53 offset:16384
	ds_read_b128 v[76:79], v53 offset:20480
	s_waitcnt vmcnt(0)
	s_waitcnt lgkmcnt(0)
	s_barrier
; #define MFMA(a, b, c) __builtin_amdgcn_mfma_f32_32x32x16_bf16((a), (b), (c), 0, 0, 0)
; template <int AI, int BI>
; DI void gemm_tile(const u16* __restrict__ A, int lda, const u16* __restrict__ B, int ldb, int nk, bool swap,
;                   f32x16 (&acc)[AI][BI], char* lds) {
;     ...
;   for (int kt = 0; kt < nk; ++kt) {
;     const char* cur = lds + (kt & 1) * 32768;
;     if (kt + 1 < nk) gemm_stage<AI, BI>(A + (kt + 1) * 64, lda, B + (kt + 1) * 64, ldb, lds + ((kt + 1) & 1) * 32768, tid);
; #pragma unroll
;     for (int ks = 0; ks < 4; ++ks) {
;       const int co = ((ks * 2 + h) ^ sw) << 4;
;       s16x8 fa[AI], fb[BI];
; #pragma unroll
;       for (int i = 0; i < AI; ++i) fa[i] = *(const s16x8*)(cur + offA + i * 4096 + co);
; #pragma unroll
;       for (int i = 0; i < BI; ++i) fb[i] = *(const s16x8*)(cur + offB + i * 4096 + co);
; #pragma unroll
;       for (int i = 0; i < AI; ++i)
; #pragma unroll
;         for (int j = 0; j < BI; ++j) acc[i][j] = MFMA(fa[i], fb[j], acc[i][j]);
;     }
;     asm volatile("s_waitcnt vmcnt(0)" ::: "memory");
;     __syncthreads();
;   }
	v_mfma_f32_32x32x16_bf16 v[2:17], v[68:71], v[72:75], v[2:17]
	v_mfma_f32_32x32x16_bf16 v[18:33], v[68:71], v[76:79], v[18:33]
	v_lshl_add_u64 v[68:69], v[34:35], 0, s[4:5]
	global_load_lds_dwordx4 v[68:69], off
	v_lshl_add_u64 v[68:69], v[36:37], 0, s[4:5]
	s_mov_b32 m0, s18
	s_nop 0
	global_load_lds_dwordx4 v[68:69], off
	v_lshl_add_u64 v[68:69], v[40:41], 0, s[4:5]
	s_mov_b32 m0, s28
	s_nop 0
	global_load_lds_dwordx4 v[68:69], off
	v_lshl_add_u64 v[68:69], v[38:39], 0, s[4:5]
	s_mov_b32 m0, s29
	s_nop 0
	global_load_lds_dwordx4 v[68:69], off
	v_lshl_add_u64 v[68:69], v[42:43], 0, s[4:5]
	s_mov_b32 m0, s34
	s_nop 0
	global_load_lds_dwordx4 v[68:69], off
	v_lshl_add_u64 v[68:69], v[44:45], 0, s[4:5]
	s_mov_b32 m0, s41
	s_nop 0
	global_load_lds_dwordx4 v[68:69], off
	ds_read_b128 v[68:71], v0 offset:32768
	ds_read_b128 v[72:75], v50 offset:49152
	ds_read_b128 v[76:79], v50 offset:53248
	s_waitcnt lgkmcnt(0)
	v_mfma_f32_32x32x16_bf16 v[2:17], v[68:71], v[72:75], v[2:17]
	s_mov_b32 m0, s35
	v_mfma_f32_32x32x16_bf16 v[18:33], v[68:71], v[76:79], v[18:33]
	ds_read_b128 v[68:71], v48 offset:32768
	ds_read_b128 v[72:75], v49 offset:49152
	ds_read_b128 v[76:79], v49 offset:53248
	s_waitcnt lgkmcnt(1)
	v_mfma_f32_32x32x16_bf16 v[2:17], v[68:71], v[72:75], v[2:17]
	s_waitcnt lgkmcnt(0)
	v_mfma_f32_32x32x16_bf16 v[18:33], v[68:71], v[76:79], v[18:33]
	ds_read_b128 v[68:71], v52 offset:32768
	ds_read_b128 v[72:75], v51 offset:49152
	ds_read_b128 v[76:79], v51 offset:53248
	s_waitcnt lgkmcnt(1)
	v_mfma_f32_32x32x16_bf16 v[2:17], v[68:71], v[72:75], v[2:17]
	s_waitcnt lgkmcnt(0)
	v_mfma_f32_32x32x16_bf16 v[18:33], v[68:71], v[76:79], v[18:33]
	ds_read_b128 v[68:71], v54 offset:32768
	ds_read_b128 v[72:75], v53 offset:49152
	ds_read_b128 v[76:79], v53 offset:53248
	s_waitcnt vmcnt(0)
	s_waitcnt lgkmcnt(0)
	s_barrier
	v_mfma_f32_32x32x16_bf16 v[2:17], v[68:71], v[72:75], v[2:17]
	v_mfma_f32_32x32x16_bf16 v[18:33], v[68:71], v[76:79], v[18:33]
	v_lshl_add_u64 v[68:69], v[34:35], 0, s[54:55]
	global_load_lds_dwordx4 v[68:69], off
	v_lshl_add_u64 v[68:69], v[36:37], 0, s[54:55]
	s_mov_b32 m0, s36
	s_nop 0
	global_load_lds_dwordx4 v[68:69], off
	v_lshl_add_u64 v[68:69], v[40:41], 0, s[54:55]
	s_mov_b32 m0, s37
	s_nop 0
	global_load_lds_dwordx4 v[68:69], off
	v_lshl_add_u64 v[68:69], v[38:39], 0, s[54:55]
	s_mov_b32 m0, s40
	s_nop 0
	global_load_lds_dwordx4 v[68:69], off
	v_lshl_add_u64 v[68:69], v[42:43], 0, s[54:55]
	s_mov_b32 m0, s46
	s_nop 0
	global_load_lds_dwordx4 v[68:69], off
	v_lshl_add_u64 v[68:69], v[44:45], 0, s[54:55]
	s_mov_b32 m0, s47
	s_nop 0
	global_load_lds_dwordx4 v[68:69], off
	ds_read_b128 v[68:71], v0
	ds_read_b128 v[72:75], v50 offset:16384
	ds_read_b128 v[76:79], v50 offset:20480
	s_waitcnt lgkmcnt(0)
	v_mfma_f32_32x32x16_bf16 v[2:17], v[68:71], v[72:75], v[2:17]
	s_mov_b32 m0, s9
	v_mfma_f32_32x32x16_bf16 v[18:33], v[68:71], v[76:79], v[18:33]
	ds_read_b128 v[68:71], v48
	ds_read_b128 v[72:75], v49 offset:16384
	ds_read_b128 v[76:79], v49 offset:20480
	s_waitcnt lgkmcnt(1)
	v_mfma_f32_32x32x16_bf16 v[2:17], v[68:71], v[72:75], v[2:17]
	s_waitcnt lgkmcnt(0)
	v_mfma_f32_32x32x16_bf16 v[18:33], v[68:71], v[76:79], v[18:33]
	ds_read_b128 v[68:71], v52
	ds_read_b128 v[72:75], v51 offset:16384
	ds_read_b128 v[76:79], v51 offset:20480
	s_waitcnt lgkmcnt(1)
	v_mfma_f32_32x32x16_bf16 v[2:17], v[68:71], v[72:75], v[2:17]
	s_waitcnt lgkmcnt(0)
	v_mfma_f32_32x32x16_bf16 v[18:33], v[68:71], v[76:79], v[18:33]
	ds_read_b128 v[68:71], v54
	ds_read_b128 v[72:75], v53 offset:16384
	ds_read_b128 v[76:79], v53 offset:20480
	s_waitcnt vmcnt(0)
	s_waitcnt lgkmcnt(0)
	s_barrier
	v_mfma_f32_32x32x16_bf16 v[2:17], v[68:71], v[72:75], v[2:17]
	v_mfma_f32_32x32x16_bf16 v[18:33], v[68:71], v[76:79], v[18:33]
	v_lshl_add_u64 v[68:69], v[34:35], 0, s[50:51]
	global_load_lds_dwordx4 v[68:69], off
	v_lshl_add_u64 v[68:69], v[36:37], 0, s[50:51]
	s_mov_b32 m0, s18
	s_nop 0
	global_load_lds_dwordx4 v[68:69], off
	v_lshl_add_u64 v[68:69], v[40:41], 0, s[50:51]
	s_mov_b32 m0, s28
	s_nop 0
	global_load_lds_dwordx4 v[68:69], off
	v_lshl_add_u64 v[68:69], v[38:39], 0, s[50:51]
	s_mov_b32 m0, s29
	s_nop 0
	global_load_lds_dwordx4 v[68:69], off
	v_lshl_add_u64 v[68:69], v[42:43], 0, s[50:51]
	s_mov_b32 m0, s34
	s_nop 0
	global_load_lds_dwordx4 v[68:69], off
	v_lshl_add_u64 v[68:69], v[44:45], 0, s[50:51]
	s_mov_b32 m0, s41
	s_nop 0
	global_load_lds_dwordx4 v[68:69], off
	ds_read_b128 v[68:71], v0 offset:32768
	ds_read_b128 v[72:75], v50 offset:49152
	ds_read_b128 v[76:79], v50 offset:53248
	s_waitcnt lgkmcnt(0)
	v_mfma_f32_32x32x16_bf16 v[2:17], v[68:71], v[72:75], v[2:17]
	s_mov_b32 m0, s35
	v_mfma_f32_32x32x16_bf16 v[18:33], v[68:71], v[76:79], v[18:33]
	ds_read_b128 v[68:71], v48 offset:32768
	ds_read_b128 v[72:75], v49 offset:49152
	ds_read_b128 v[76:79], v49 offset:53248
	s_waitcnt lgkmcnt(1)
	v_mfma_f32_32x32x16_bf16 v[2:17], v[68:71], v[72:75], v[2:17]
	s_waitcnt lgkmcnt(0)
	v_mfma_f32_32x32x16_bf16 v[18:33], v[68:71], v[76:79], v[18:33]
	ds_read_b128 v[68:71], v52 offset:32768
	ds_read_b128 v[72:75], v51 offset:49152
	ds_read_b128 v[76:79], v51 offset:53248
	s_waitcnt lgkmcnt(1)
	v_mfma_f32_32x32x16_bf16 v[2:17], v[68:71], v[72:75], v[2:17]
	s_waitcnt lgkmcnt(0)
	v_mfma_f32_32x32x16_bf16 v[18:33], v[68:71], v[76:79], v[18:33]
	ds_read_b128 v[68:71], v54 offset:32768
	ds_read_b128 v[72:75], v53 offset:49152
	ds_read_b128 v[76:79], v53 offset:53248
	s_waitcnt vmcnt(0)
	s_waitcnt lgkmcnt(0)
	s_barrier
; #define MFMA(a, b, c) __builtin_amdgcn_mfma_f32_32x32x16_bf16((a), (b), (c), 0, 0, 0)
; template <int AI, int BI>
; DI void gemm_tile(const u16* __restrict__ A, int lda, const u16* __restrict__ B, int ldb, int nk, bool swap,
;                   f32x16 (&acc)[AI][BI], char* lds) {
;     ...
;   for (int kt = 0; kt < nk; ++kt) {
;     const char* cur = lds + (kt & 1) * 32768;
;     if (kt + 1 < nk) gemm_stage<AI, BI>(A + (kt + 1) * 64, lda, B + (kt + 1) * 64, ldb, lds + ((kt + 1) & 1) * 32768, tid);
; #pragma unroll
;     for (int ks = 0; ks < 4; ++ks) {
;       const int co = ((ks * 2 + h) ^ sw) << 4;
;       s16x8 fa[AI], fb[BI];
; #pragma unroll
;       for (int i = 0; i < AI; ++i) fa[i] = *(const s16x8*)(cur + offA + i * 4096 + co);
; #pragma unroll
;       for (int i = 0; i < BI; ++i) fb[i] = *(const s16x8*)(cur + offB + i * 4096 + co);
; #pragma unroll
;       for (int i = 0; i < AI; ++i)
; #pragma unroll
;         for (int j = 0; j < BI; ++j) acc[i][j] = MFMA(fa[i], fb[j], acc[i][j]);
;     }
;     asm volatile("s_waitcnt vmcnt(0)" ::: "memory");
;     __syncthreads();
;   }
	v_mfma_f32_32x32x16_bf16 v[2:17], v[68:71], v[72:75], v[2:17]
	v_mfma_f32_32x32x16_bf16 v[18:33], v[68:71], v[76:79], v[18:33]
	v_lshl_add_u64 v[68:69], v[34:35], 0, s[56:57]
	global_load_lds_dwordx4 v[68:69], off
	v_lshl_add_u64 v[68:69], v[36:37], 0, s[56:57]
	s_mov_b32 m0, s36
	s_nop 0
	global_load_lds_dwordx4 v[68:69], off
	v_lshl_add_u64 v[68:69], v[40:41], 0, s[56:57]
	s_mov_b32 m0, s37
	s_nop 0
	global_load_lds_dwordx4 v[68:69], off
	v_lshl_add_u64 v[68:69], v[38:39], 0, s[56:57]
	s_mov_b32 m0, s40
	s_nop 0
	global_load_lds_dwordx4 v[68:69], off
	v_lshl_add_u64 v[68:69], v[42:43], 0, s[56:57]
	s_mov_b32 m0, s46
	s_nop 0
	global_load_lds_dwordx4 v[68:69], off
	v_lshl_add_u64 v[68:69], v[44:45], 0, s[56:57]
	s_mov_b32 m0, s47
	s_nop 0
	global_load_lds_dwordx4 v[68:69], off
	ds_read_b128 v[68:71], v0
	ds_read_b128 v[72:75], v50 offset:16384
	ds_read_b128 v[76:79], v50 offset:20480
	s_waitcnt lgkmcnt(0)
	v_mfma_f32_32x32x16_bf16 v[2:17], v[68:71], v[72:75], v[2:17]
	s_mov_b32 m0, s9
	v_mfma_f32_32x32x16_bf16 v[18:33], v[68:71], v[76:79], v[18:33]
	ds_read_b128 v[68:71], v48
	ds_read_b128 v[72:75], v49 offset:16384
	ds_read_b128 v[76:79], v49 offset:20480
	s_waitcnt lgkmcnt(1)
	v_mfma_f32_32x32x16_bf16 v[2:17], v[68:71], v[72:75], v[2:17]
	s_waitcnt lgkmcnt(0)
	v_mfma_f32_32x32x16_bf16 v[18:33], v[68:71], v[76:79], v[18:33]
	ds_read_b128 v[68:71], v52
	ds_read_b128 v[72:75], v51 offset:16384
	ds_read_b128 v[76:79], v51 offset:20480
	s_waitcnt lgkmcnt(1)
	v_mfma_f32_32x32x16_bf16 v[2:17], v[68:71], v[72:75], v[2:17]
	s_waitcnt lgkmcnt(0)
	v_mfma_f32_32x32x16_bf16 v[18:33], v[68:71], v[76:79], v[18:33]
	ds_read_b128 v[68:71], v54
	ds_read_b128 v[72:75], v53 offset:16384
	ds_read_b128 v[76:79], v53 offset:20480
	s_waitcnt vmcnt(0)
	s_waitcnt lgkmcnt(0)
	s_barrier
	v_mfma_f32_32x32x16_bf16 v[2:17], v[68:71], v[72:75], v[2:17]
	v_mfma_f32_32x32x16_bf16 v[18:33], v[68:71], v[76:79], v[18:33]
	v_lshl_add_u64 v[68:69], v[34:35], 0, s[64:65]
	global_load_lds_dwordx4 v[68:69], off
	v_lshl_add_u64 v[68:69], v[36:37], 0, s[64:65]
	s_mov_b32 m0, s18
	s_nop 0
	global_load_lds_dwordx4 v[68:69], off
	v_lshl_add_u64 v[68:69], v[40:41], 0, s[64:65]
	s_mov_b32 m0, s28
	s_nop 0
	global_load_lds_dwordx4 v[68:69], off
	v_lshl_add_u64 v[68:69], v[38:39], 0, s[64:65]
	s_mov_b32 m0, s29
	s_nop 0
	global_load_lds_dwordx4 v[68:69], off
	v_lshl_add_u64 v[68:69], v[42:43], 0, s[64:65]
	s_mov_b32 m0, s34
	s_nop 0
	global_load_lds_dwordx4 v[68:69], off
	v_lshl_add_u64 v[68:69], v[44:45], 0, s[64:65]
	s_mov_b32 m0, s41
	s_nop 0
	global_load_lds_dwordx4 v[68:69], off
	ds_read_b128 v[68:71], v0 offset:32768
	ds_read_b128 v[72:75], v50 offset:49152
	ds_read_b128 v[76:79], v50 offset:53248
	s_waitcnt lgkmcnt(0)
	v_mfma_f32_32x32x16_bf16 v[2:17], v[68:71], v[72:75], v[2:17]
	s_mov_b32 m0, s35
	v_mfma_f32_32x32x16_bf16 v[18:33], v[68:71], v[76:79], v[18:33]
	ds_read_b128 v[68:71], v48 offset:32768
	ds_read_b128 v[72:75], v49 offset:49152
	ds_read_b128 v[76:79], v49 offset:53248
	s_waitcnt lgkmcnt(1)
	v_mfma_f32_32x32x16_bf16 v[2:17], v[68:71], v[72:75], v[2:17]
	s_waitcnt lgkmcnt(0)
	v_mfma_f32_32x32x16_bf16 v[18:33], v[68:71], v[76:79], v[18:33]
	ds_read_b128 v[68:71], v52 offset:32768
	ds_read_b128 v[72:75], v51 offset:49152
	ds_read_b128 v[76:79], v51 offset:53248
	s_waitcnt lgkmcnt(1)
	v_mfma_f32_32x32x16_bf16 v[2:17], v[68:71], v[72:75], v[2:17]
	s_waitcnt lgkmcnt(0)
	v_mfma_f32_32x32x16_bf16 v[18:33], v[68:71], v[76:79], v[18:33]
	ds_read_b128 v[68:71], v54 offset:32768
	ds_read_b128 v[72:75], v53 offset:49152
	ds_read_b128 v[76:79], v53 offset:53248
	s_waitcnt vmcnt(0)
	s_waitcnt lgkmcnt(0)
	s_barrier
	v_mfma_f32_32x32x16_bf16 v[2:17], v[68:71], v[72:75], v[2:17]
	v_mfma_f32_32x32x16_bf16 v[18:33], v[68:71], v[76:79], v[18:33]
	v_lshl_add_u64 v[68:69], v[34:35], 0, s[66:67]
	global_load_lds_dwordx4 v[68:69], off
	v_lshl_add_u64 v[68:69], v[36:37], 0, s[66:67]
	s_mov_b32 m0, s36
	s_nop 0
	global_load_lds_dwordx4 v[68:69], off
	v_lshl_add_u64 v[68:69], v[40:41], 0, s[66:67]
	s_mov_b32 m0, s37
	s_nop 0
	global_load_lds_dwordx4 v[68:69], off
	v_lshl_add_u64 v[68:69], v[38:39], 0, s[66:67]
	s_mov_b32 m0, s40
	s_nop 0
	global_load_lds_dwordx4 v[68:69], off
	v_lshl_add_u64 v[68:69], v[42:43], 0, s[66:67]
	s_mov_b32 m0, s46
	s_nop 0
	global_load_lds_dwordx4 v[68:69], off
	v_lshl_add_u64 v[68:69], v[44:45], 0, s[66:67]
	s_mov_b32 m0, s47
	s_nop 0
	global_load_lds_dwordx4 v[68:69], off
	ds_read_b128 v[68:71], v0
	ds_read_b128 v[72:75], v50 offset:16384
	ds_read_b128 v[76:79], v50 offset:20480
	s_waitcnt lgkmcnt(0)
	v_mfma_f32_32x32x16_bf16 v[2:17], v[68:71], v[72:75], v[2:17]
	s_mov_b32 m0, s9
	v_mfma_f32_32x32x16_bf16 v[18:33], v[68:71], v[76:79], v[18:33]
	ds_read_b128 v[68:71], v48
	ds_read_b128 v[72:75], v49 offset:16384
	ds_read_b128 v[76:79], v49 offset:20480
	s_waitcnt lgkmcnt(1)
	v_mfma_f32_32x32x16_bf16 v[2:17], v[68:71], v[72:75], v[2:17]
	s_waitcnt lgkmcnt(0)
	v_mfma_f32_32x32x16_bf16 v[18:33], v[68:71], v[76:79], v[18:33]
	ds_read_b128 v[68:71], v52
	ds_read_b128 v[72:75], v51 offset:16384
	ds_read_b128 v[76:79], v51 offset:20480
	s_waitcnt lgkmcnt(1)
	v_mfma_f32_32x32x16_bf16 v[2:17], v[68:71], v[72:75], v[2:17]
	s_waitcnt lgkmcnt(0)
	v_mfma_f32_32x32x16_bf16 v[18:33], v[68:71], v[76:79], v[18:33]
	ds_read_b128 v[68:71], v54
	ds_read_b128 v[72:75], v53 offset:16384
	ds_read_b128 v[76:79], v53 offset:20480
	s_waitcnt vmcnt(0)
	s_waitcnt lgkmcnt(0)
	s_barrier
; #define MFMA(a, b, c) __builtin_amdgcn_mfma_f32_32x32x16_bf16((a), (b), (c), 0, 0, 0)
; template <int AI, int BI>
; DI void gemm_tile(const u16* __restrict__ A, int lda, const u16* __restrict__ B, int ldb, int nk, bool swap,
;                   f32x16 (&acc)[AI][BI], char* lds) {
;     ...
;   for (int kt = 0; kt < nk; ++kt) {
;     const char* cur = lds + (kt & 1) * 32768;
;     if (kt + 1 < nk) gemm_stage<AI, BI>(A + (kt + 1) * 64, lda, B + (kt + 1) * 64, ldb, lds + ((kt + 1) & 1) * 32768, tid);
; #pragma unroll
;     for (int ks = 0; ks < 4; ++ks) {
;       const int co = ((ks * 2 + h) ^ sw) << 4;
;       s16x8 fa[AI], fb[BI];
; #pragma unroll
;       for (int i = 0; i < AI; ++i) fa[i] = *(const s16x8*)(cur + offA + i * 4096 + co);
; #pragma unroll
;       for (int i = 0; i < BI; ++i) fb[i] = *(const s16x8*)(cur + offB + i * 4096 + co);
; #pragma unroll
;       for (int i = 0; i < AI; ++i)
; #pragma unroll
;         for (int j = 0; j < BI; ++j) acc[i][j] = MFMA(fa[i], fb[j], acc[i][j]);
;     }
;     asm volatile("s_waitcnt vmcnt(0)" ::: "memory");
;     __syncthreads();
;   }
	v_mfma_f32_32x32x16_bf16 v[2:17], v[68:71], v[72:75], v[2:17]
	v_mfma_f32_32x32x16_bf16 v[18:33], v[68:71], v[76:79], v[18:33]
	v_lshl_add_u64 v[68:69], v[34:35], 0, s[68:69]
	global_load_lds_dwordx4 v[68:69], off
	v_lshl_add_u64 v[68:69], v[36:37], 0, s[68:69]
	s_mov_b32 m0, s18
	s_nop 0
	global_load_lds_dwordx4 v[68:69], off
	v_lshl_add_u64 v[68:69], v[40:41], 0, s[68:69]
	s_mov_b32 m0, s28
	s_nop 0
	global_load_lds_dwordx4 v[68:69], off
	v_lshl_add_u64 v[68:69], v[38:39], 0, s[68:69]
	s_mov_b32 m0, s29
	s_nop 0
	global_load_lds_dwordx4 v[68:69], off
	v_lshl_add_u64 v[68:69], v[42:43], 0, s[68:69]
	s_mov_b32 m0, s34
	s_nop 0
	global_load_lds_dwordx4 v[68:69], off
	v_lshl_add_u64 v[68:69], v[44:45], 0, s[68:69]
	s_mov_b32 m0, s41
	s_nop 0
	global_load_lds_dwordx4 v[68:69], off
	ds_read_b128 v[68:71], v0 offset:32768
	ds_read_b128 v[72:75], v50 offset:49152
	ds_read_b128 v[76:79], v50 offset:53248
	s_waitcnt lgkmcnt(0)
	v_mfma_f32_32x32x16_bf16 v[2:17], v[68:71], v[72:75], v[2:17]
	s_mov_b32 m0, s35
	v_mfma_f32_32x32x16_bf16 v[18:33], v[68:71], v[76:79], v[18:33]
	ds_read_b128 v[68:71], v48 offset:32768
	ds_read_b128 v[72:75], v49 offset:49152
	ds_read_b128 v[76:79], v49 offset:53248
	s_waitcnt lgkmcnt(1)
	v_mfma_f32_32x32x16_bf16 v[2:17], v[68:71], v[72:75], v[2:17]
	s_waitcnt lgkmcnt(0)
	v_mfma_f32_32x32x16_bf16 v[18:33], v[68:71], v[76:79], v[18:33]
	ds_read_b128 v[68:71], v52 offset:32768
	ds_read_b128 v[72:75], v51 offset:49152
	ds_read_b128 v[76:79], v51 offset:53248
	s_waitcnt lgkmcnt(1)
	v_mfma_f32_32x32x16_bf16 v[2:17], v[68:71], v[72:75], v[2:17]
	s_waitcnt lgkmcnt(0)
	v_mfma_f32_32x32x16_bf16 v[18:33], v[68:71], v[76:79], v[18:33]
	ds_read_b128 v[68:71], v54 offset:32768
	ds_read_b128 v[72:75], v53 offset:49152
	ds_read_b128 v[76:79], v53 offset:53248
	s_waitcnt vmcnt(0)
	s_waitcnt lgkmcnt(0)
	s_barrier
	v_mfma_f32_32x32x16_bf16 v[2:17], v[68:71], v[72:75], v[2:17]
	v_mfma_f32_32x32x16_bf16 v[18:33], v[68:71], v[76:79], v[18:33]
	v_lshl_add_u64 v[68:69], v[34:35], 0, s[70:71]
	global_load_lds_dwordx4 v[68:69], off
	v_lshl_add_u64 v[68:69], v[36:37], 0, s[70:71]
	s_mov_b32 m0, s36
	s_nop 0
	global_load_lds_dwordx4 v[68:69], off
	v_lshl_add_u64 v[68:69], v[40:41], 0, s[70:71]
	s_mov_b32 m0, s37
	s_nop 0
	global_load_lds_dwordx4 v[68:69], off
	v_lshl_add_u64 v[68:69], v[38:39], 0, s[70:71]
	s_mov_b32 m0, s40
	s_nop 0
	global_load_lds_dwordx4 v[68:69], off
	v_lshl_add_u64 v[68:69], v[42:43], 0, s[70:71]
	s_mov_b32 m0, s46
	s_nop 0
	global_load_lds_dwordx4 v[68:69], off
	v_lshl_add_u64 v[68:69], v[44:45], 0, s[70:71]
	s_mov_b32 m0, s47
	s_nop 0
	global_load_lds_dwordx4 v[68:69], off
	ds_read_b128 v[68:71], v0
	ds_read_b128 v[72:75], v50 offset:16384
	ds_read_b128 v[76:79], v50 offset:20480
	s_waitcnt lgkmcnt(0)
	v_mfma_f32_32x32x16_bf16 v[2:17], v[68:71], v[72:75], v[2:17]
	s_mov_b32 m0, s9
	v_readfirstlane_b32 s9, v55
	v_and_b32_e32 v55, 31, v46
	v_mfma_f32_32x32x16_bf16 v[18:33], v[68:71], v[76:79], v[18:33]
	ds_read_b128 v[68:71], v48
	ds_read_b128 v[72:75], v49 offset:16384
	ds_read_b128 v[76:79], v49 offset:20480
	s_waitcnt lgkmcnt(1)
	v_mfma_f32_32x32x16_bf16 v[2:17], v[68:71], v[72:75], v[2:17]
	s_waitcnt lgkmcnt(0)
	v_mfma_f32_32x32x16_bf16 v[18:33], v[68:71], v[76:79], v[18:33]
	ds_read_b128 v[68:71], v52
	ds_read_b128 v[72:75], v51 offset:16384
	ds_read_b128 v[76:79], v51 offset:20480
	s_waitcnt lgkmcnt(1)
	v_mfma_f32_32x32x16_bf16 v[2:17], v[68:71], v[72:75], v[2:17]
	s_waitcnt lgkmcnt(0)
	v_mfma_f32_32x32x16_bf16 v[18:33], v[68:71], v[76:79], v[18:33]
	ds_read_b128 v[68:71], v54
	ds_read_b128 v[72:75], v53 offset:16384
	ds_read_b128 v[76:79], v53 offset:20480
	s_waitcnt vmcnt(0)
	s_waitcnt lgkmcnt(0)
	s_barrier
	v_mfma_f32_32x32x16_bf16 v[2:17], v[68:71], v[72:75], v[2:17]
	v_mfma_f32_32x32x16_bf16 v[18:33], v[68:71], v[76:79], v[18:33]
	v_lshl_add_u64 v[68:69], v[34:35], 0, s[72:73]
	global_load_lds_dwordx4 v[68:69], off
	v_lshl_add_u64 v[68:69], v[36:37], 0, s[72:73]
	s_mov_b32 m0, s18
	v_readfirstlane_b32 s18, v56
	global_load_lds_dwordx4 v[68:69], off
	v_lshl_add_u64 v[68:69], v[40:41], 0, s[72:73]
	s_mov_b32 m0, s28
	v_readfirstlane_b32 s28, v57
	global_load_lds_dwordx4 v[68:69], off
	v_lshl_add_u64 v[68:69], v[38:39], 0, s[72:73]
	s_mov_b32 m0, s29
	v_readfirstlane_b32 s29, v58
	global_load_lds_dwordx4 v[68:69], off
	v_lshl_add_u64 v[68:69], v[42:43], 0, s[72:73]
	s_mov_b32 m0, s34
	v_lshl_add_u64 v[56:57], v[38:39], 0, s[76:77]
	global_load_lds_dwordx4 v[68:69], off
	v_lshl_add_u64 v[68:69], v[44:45], 0, s[72:73]
	s_mov_b32 m0, s41
	v_readfirstlane_b32 s34, v65
	global_load_lds_dwordx4 v[68:69], off
	ds_read_b128 v[68:71], v0 offset:32768
	ds_read_b128 v[72:75], v50 offset:49152
	ds_read_b128 v[76:79], v50 offset:53248
	s_waitcnt lgkmcnt(0)
	v_mfma_f32_32x32x16_bf16 v[2:17], v[68:71], v[72:75], v[2:17]
	s_mov_b32 m0, s35
	v_readfirstlane_b32 s35, v66
	v_readfirstlane_b32 s41, v61
	v_mfma_f32_32x32x16_bf16 v[18:33], v[68:71], v[76:79], v[18:33]
	ds_read_b128 v[68:71], v48 offset:32768
	ds_read_b128 v[72:75], v49 offset:49152
	ds_read_b128 v[76:79], v49 offset:53248
	s_waitcnt lgkmcnt(1)
	v_mfma_f32_32x32x16_bf16 v[2:17], v[68:71], v[72:75], v[2:17]
	s_waitcnt lgkmcnt(0)
	v_mfma_f32_32x32x16_bf16 v[18:33], v[68:71], v[76:79], v[18:33]
	ds_read_b128 v[68:71], v52 offset:32768
	ds_read_b128 v[72:75], v51 offset:49152
	ds_read_b128 v[76:79], v51 offset:53248
	s_waitcnt lgkmcnt(1)
	v_mfma_f32_32x32x16_bf16 v[2:17], v[68:71], v[72:75], v[2:17]
	s_waitcnt lgkmcnt(0)
	v_mfma_f32_32x32x16_bf16 v[18:33], v[68:71], v[76:79], v[18:33]
	ds_read_b128 v[68:71], v54 offset:32768
	ds_read_b128 v[72:75], v53 offset:49152
	ds_read_b128 v[76:79], v53 offset:53248
	s_waitcnt vmcnt(0)
	s_waitcnt lgkmcnt(0)
	s_barrier
; #define MFMA(a, b, c) __builtin_amdgcn_mfma_f32_32x32x16_bf16((a), (b), (c), 0, 0, 0)
; template <int AI, int BI>
; DI void gemm_tile(const u16* __restrict__ A, int lda, const u16* __restrict__ B, int ldb, int nk, bool swap,
;                   f32x16 (&acc)[AI][BI], char* lds) {
;     ...
;   for (int kt = 0; kt < nk; ++kt) {
;     const char* cur = lds + (kt & 1) * 32768;
;     if (kt + 1 < nk) gemm_stage<AI, BI>(A + (kt + 1) * 64, lda, B + (kt + 1) * 64, ldb, lds + ((kt + 1) & 1) * 32768, tid);
; #pragma unroll
;     for (int ks = 0; ks < 4; ++ks) {
;       const int co = ((ks * 2 + h) ^ sw) << 4;
;       s16x8 fa[AI], fb[BI];
; #pragma unroll
;       for (int i = 0; i < AI; ++i) fa[i] = *(const s16x8*)(cur + offA + i * 4096 + co);
; #pragma unroll
;       for (int i = 0; i < BI; ++i) fb[i] = *(const s16x8*)(cur + offB + i * 4096 + co);
; #pragma unroll
;       for (int i = 0; i < AI; ++i)
; #pragma unroll
;         for (int j = 0; j < BI; ++j) acc[i][j] = MFMA(fa[i], fb[j], acc[i][j]);
;     }
;     asm volatile("s_waitcnt vmcnt(0)" ::: "memory");
;     __syncthreads();
;   }
	v_mfma_f32_32x32x16_bf16 v[2:17], v[68:71], v[72:75], v[2:17]
	v_mfma_f32_32x32x16_bf16 v[18:33], v[68:71], v[76:79], v[18:33]
	v_lshl_add_u64 v[68:69], v[34:35], 0, s[74:75]
	global_load_lds_dwordx4 v[68:69], off
	v_lshl_add_u64 v[68:69], v[36:37], 0, s[74:75]
	s_mov_b32 m0, s36
	v_readfirstlane_b32 s36, v63
	global_load_lds_dwordx4 v[68:69], off
	v_lshl_add_u64 v[68:69], v[40:41], 0, s[74:75]
	s_mov_b32 m0, s37
	v_readfirstlane_b32 s37, v60
	global_load_lds_dwordx4 v[68:69], off
	v_lshl_add_u64 v[68:69], v[38:39], 0, s[74:75]
	s_mov_b32 m0, s40
	v_readfirstlane_b32 s40, v59
	global_load_lds_dwordx4 v[68:69], off
	v_lshl_add_u64 v[68:69], v[42:43], 0, s[74:75]
	s_mov_b32 m0, s46
	v_readfirstlane_b32 s46, v62
	global_load_lds_dwordx4 v[68:69], off
	v_lshl_add_u64 v[68:69], v[44:45], 0, s[74:75]
	s_mov_b32 m0, s47
	v_readfirstlane_b32 s47, v64
	global_load_lds_dwordx4 v[68:69], off
	ds_read_b128 v[68:71], v0
	ds_read_b128 v[72:75], v50 offset:16384
	ds_read_b128 v[76:79], v50 offset:20480
	s_waitcnt lgkmcnt(0)
	v_mfma_f32_32x32x16_bf16 v[2:17], v[68:71], v[72:75], v[2:17]
	s_mov_b32 m0, s9
	v_mfma_f32_32x32x16_bf16 v[18:33], v[68:71], v[76:79], v[18:33]
	ds_read_b128 v[68:71], v48
	ds_read_b128 v[72:75], v49 offset:16384
	ds_read_b128 v[76:79], v49 offset:20480
	s_waitcnt lgkmcnt(1)
	v_mfma_f32_32x32x16_bf16 v[2:17], v[68:71], v[72:75], v[2:17]
	s_waitcnt lgkmcnt(0)
	v_mfma_f32_32x32x16_bf16 v[18:33], v[68:71], v[76:79], v[18:33]
	ds_read_b128 v[68:71], v52
	ds_read_b128 v[72:75], v51 offset:16384
	ds_read_b128 v[76:79], v51 offset:20480
	s_waitcnt lgkmcnt(1)
	v_mfma_f32_32x32x16_bf16 v[2:17], v[68:71], v[72:75], v[2:17]
	s_waitcnt lgkmcnt(0)
	v_mfma_f32_32x32x16_bf16 v[18:33], v[68:71], v[76:79], v[18:33]
	ds_read_b128 v[68:71], v54
	ds_read_b128 v[72:75], v53 offset:16384
	ds_read_b128 v[76:79], v53 offset:20480
	s_waitcnt vmcnt(0)
	s_waitcnt lgkmcnt(0)
	s_barrier
	v_mfma_f32_32x32x16_bf16 v[2:17], v[68:71], v[72:75], v[2:17]
	v_mfma_f32_32x32x16_bf16 v[18:33], v[68:71], v[76:79], v[18:33]
	v_lshl_add_u64 v[68:69], v[34:35], 0, s[76:77]
	global_load_lds_dwordx4 v[68:69], off
	v_lshl_add_u64 v[68:69], v[36:37], 0, s[76:77]
	s_mov_b32 m0, s18
	s_nop 0
	global_load_lds_dwordx4 v[68:69], off
	v_lshl_add_u64 v[68:69], v[40:41], 0, s[76:77]
	s_mov_b32 m0, s28
	s_nop 0
	global_load_lds_dwordx4 v[68:69], off
	s_mov_b32 m0, s29
	s_nop 0
	global_load_lds_dwordx4 v[56:57], off
	v_lshl_add_u64 v[56:57], v[42:43], 0, s[76:77]
	s_mov_b32 m0, s34
	s_nop 0
	global_load_lds_dwordx4 v[56:57], off
	v_lshl_add_u64 v[56:57], v[44:45], 0, s[76:77]
	s_mov_b32 m0, s35
	s_nop 0
	global_load_lds_dwordx4 v[56:57], off
	ds_read_b128 v[66:69], v0 offset:32768
	ds_read_b128 v[70:73], v50 offset:49152
	ds_read_b128 v[74:77], v50 offset:53248
	s_waitcnt lgkmcnt(0)
	v_mfma_f32_32x32x16_bf16 v[2:17], v[66:69], v[70:73], v[2:17]
	v_lshl_add_u64 v[56:57], v[34:35], 0, s[78:79]
	s_mov_b32 m0, s36
	v_mfma_f32_32x32x16_bf16 v[18:33], v[66:69], v[74:77], v[18:33]
	ds_read_b128 v[66:69], v48 offset:32768
	ds_read_b128 v[70:73], v49 offset:49152
	ds_read_b128 v[74:77], v49 offset:53248
	s_waitcnt lgkmcnt(1)
	v_mfma_f32_32x32x16_bf16 v[2:17], v[66:69], v[70:73], v[2:17]
	s_waitcnt lgkmcnt(0)
	v_mfma_f32_32x32x16_bf16 v[18:33], v[66:69], v[74:77], v[18:33]
	ds_read_b128 v[66:69], v52 offset:32768
	ds_read_b128 v[70:73], v51 offset:49152
	ds_read_b128 v[74:77], v51 offset:53248
	s_waitcnt lgkmcnt(1)
	v_mfma_f32_32x32x16_bf16 v[2:17], v[66:69], v[70:73], v[2:17]
	s_waitcnt lgkmcnt(0)
	v_mfma_f32_32x32x16_bf16 v[18:33], v[66:69], v[74:77], v[18:33]
	ds_read_b128 v[66:69], v54 offset:32768
	ds_read_b128 v[70:73], v53 offset:49152
	ds_read_b128 v[74:77], v53 offset:53248
	s_waitcnt vmcnt(0)
	s_waitcnt lgkmcnt(0)
	s_barrier
	global_load_lds_dwordx4 v[56:57], off
	v_lshl_add_u64 v[56:57], v[36:37], 0, s[78:79]
	s_mov_b32 m0, s37
	v_mfma_f32_32x32x16_bf16 v[2:17], v[66:69], v[70:73], v[2:17]
	global_load_lds_dwordx4 v[56:57], off
	v_lshl_add_u64 v[56:57], v[40:41], 0, s[78:79]
	s_mov_b32 m0, s40
	s_nop 0
	global_load_lds_dwordx4 v[56:57], off
	v_lshl_add_u64 v[56:57], v[38:39], 0, s[78:79]
	s_mov_b32 m0, s41
	v_mfma_f32_32x32x16_bf16 v[18:33], v[66:69], v[74:77], v[18:33]
	global_load_lds_dwordx4 v[56:57], off
	v_lshl_add_u64 v[56:57], v[42:43], 0, s[78:79]
	s_mov_b32 m0, s46
	s_nop 0
	global_load_lds_dwordx4 v[56:57], off
	v_lshl_add_u64 v[56:57], v[44:45], 0, s[78:79]
	s_mov_b32 m0, s47
	s_nop 0
	global_load_lds_dwordx4 v[56:57], off
	ds_read_b128 v[56:59], v0
	ds_read_b128 v[60:63], v50 offset:16384
	ds_read_b128 v[64:67], v50 offset:20480
	s_waitcnt lgkmcnt(0)
	v_mfma_f32_32x32x16_bf16 v[2:17], v[56:59], v[60:63], v[2:17]
	s_mov_b32 m0, s9
	s_movk_i32 s9, 0xb00
	v_mfma_f32_32x32x16_bf16 v[18:33], v[56:59], v[64:67], v[18:33]
	ds_read_b128 v[56:59], v48
	ds_read_b128 v[60:63], v49 offset:16384
	ds_read_b128 v[64:67], v49 offset:20480
	s_waitcnt lgkmcnt(1)
	v_mfma_f32_32x32x16_bf16 v[2:17], v[56:59], v[60:63], v[2:17]
	s_waitcnt lgkmcnt(0)
	v_mfma_f32_32x32x16_bf16 v[18:33], v[56:59], v[64:67], v[18:33]
	ds_read_b128 v[56:59], v52
	ds_read_b128 v[60:63], v51 offset:16384
	ds_read_b128 v[64:67], v51 offset:20480
	s_waitcnt lgkmcnt(1)
	v_mfma_f32_32x32x16_bf16 v[2:17], v[56:59], v[60:63], v[2:17]
	s_waitcnt lgkmcnt(0)
	v_mfma_f32_32x32x16_bf16 v[18:33], v[56:59], v[64:67], v[18:33]
	ds_read_b128 v[56:59], v54
	ds_read_b128 v[60:63], v53 offset:16384
	ds_read_b128 v[64:67], v53 offset:20480
	s_waitcnt vmcnt(0)
	s_waitcnt lgkmcnt(0)
	s_barrier
; #define MFMA(a, b, c) __builtin_amdgcn_mfma_f32_32x32x16_bf16((a), (b), (c), 0, 0, 0)
; template <int AI, int BI>
; DI void gemm_tile(const u16* __restrict__ A, int lda, const u16* __restrict__ B, int ldb, int nk, bool swap,
;                   f32x16 (&acc)[AI][BI], char* lds) {
;     ...
;   for (int kt = 0; kt < nk; ++kt) {
;     const char* cur = lds + (kt & 1) * 32768;
;     if (kt + 1 < nk) gemm_stage<AI, BI>(A + (kt + 1) * 64, lda, B + (kt + 1) * 64, ldb, lds + ((kt + 1) & 1) * 32768, tid);
; #pragma unroll
;     for (int ks = 0; ks < 4; ++ks) {
;       const int co = ((ks * 2 + h) ^ sw) << 4;
;       s16x8 fa[AI], fb[BI];
; #pragma unroll
;       for (int i = 0; i < AI; ++i) fa[i] = *(const s16x8*)(cur + offA + i * 4096 + co);
; #pragma unroll
;       for (int i = 0; i < BI; ++i) fb[i] = *(const s16x8*)(cur + offB + i * 4096 + co);
; #pragma unroll
;       for (int i = 0; i < AI; ++i)
; #pragma unroll
;         for (int j = 0; j < BI; ++j) acc[i][j] = MFMA(fa[i], fb[j], acc[i][j]);
;     }
;     asm volatile("s_waitcnt vmcnt(0)" ::: "memory");
;     __syncthreads();
;   }
	v_mfma_f32_32x32x16_bf16 v[2:17], v[56:59], v[60:63], v[2:17]
	v_mfma_f32_32x32x16_bf16 v[18:33], v[56:59], v[64:67], v[18:33]
	v_lshl_add_u64 v[56:57], v[34:35], 0, s[2:3]
	global_load_lds_dwordx4 v[56:57], off
	v_lshl_add_u64 v[56:57], v[36:37], 0, s[2:3]
	s_mov_b32 m0, s18
	v_lshl_add_u64 v[34:35], v[34:35], 0, s[30:31]
	global_load_lds_dwordx4 v[56:57], off
	v_lshl_add_u64 v[56:57], v[40:41], 0, s[2:3]
	s_mov_b32 m0, s28
	s_mov_b32 s18, 0xffffe0
	global_load_lds_dwordx4 v[56:57], off
	v_lshl_add_u64 v[56:57], v[38:39], 0, s[2:3]
	s_mov_b32 m0, s29
	s_nop 0
	global_load_lds_dwordx4 v[56:57], off
	v_lshl_add_u64 v[56:57], v[42:43], 0, s[2:3]
	s_mov_b32 m0, s34
	s_nop 0
	global_load_lds_dwordx4 v[56:57], off
	v_lshl_add_u64 v[56:57], v[44:45], 0, s[2:3]
	s_mov_b32 m0, s35
	s_nop 0
	global_load_lds_dwordx4 v[56:57], off
	ds_read_b128 v[56:59], v0 offset:32768
	ds_read_b128 v[60:63], v50 offset:49152
	ds_read_b128 v[64:67], v50 offset:53248
	s_waitcnt lgkmcnt(0)
	v_mfma_f32_32x32x16_bf16 v[2:17], v[56:59], v[60:63], v[2:17]
	s_mov_b32 m0, s36
	v_mfma_f32_32x32x16_bf16 v[18:33], v[56:59], v[64:67], v[18:33]
	ds_read_b128 v[56:59], v48 offset:32768
	ds_read_b128 v[60:63], v49 offset:49152
	ds_read_b128 v[64:67], v49 offset:53248
	s_waitcnt lgkmcnt(1)
	v_mfma_f32_32x32x16_bf16 v[2:17], v[56:59], v[60:63], v[2:17]
	s_waitcnt lgkmcnt(0)
	v_mfma_f32_32x32x16_bf16 v[18:33], v[56:59], v[64:67], v[18:33]
	ds_read_b128 v[56:59], v52 offset:32768
	ds_read_b128 v[60:63], v51 offset:49152
	ds_read_b128 v[64:67], v51 offset:53248
	s_waitcnt lgkmcnt(1)
	v_mfma_f32_32x32x16_bf16 v[2:17], v[56:59], v[60:63], v[2:17]
	s_waitcnt lgkmcnt(0)
	v_mfma_f32_32x32x16_bf16 v[18:33], v[56:59], v[64:67], v[18:33]
	ds_read_b128 v[56:59], v54 offset:32768
	ds_read_b128 v[60:63], v53 offset:49152
	ds_read_b128 v[64:67], v53 offset:53248
	s_waitcnt vmcnt(0)
	s_waitcnt lgkmcnt(0)
	s_barrier
	global_load_lds_dwordx4 v[34:35], off
	v_lshl_add_u64 v[34:35], v[36:37], 0, s[30:31]
	s_mov_b32 m0, s37
	v_mfma_f32_32x32x16_bf16 v[2:17], v[56:59], v[60:63], v[2:17]
	global_load_lds_dwordx4 v[34:35], off
	v_lshl_add_u64 v[34:35], v[40:41], 0, s[30:31]
	s_mov_b32 m0, s40
	s_nop 0
	global_load_lds_dwordx4 v[34:35], off
	v_lshl_add_u64 v[34:35], v[38:39], 0, s[30:31]
	s_mov_b32 m0, s41
	v_mfma_f32_32x32x16_bf16 v[18:33], v[56:59], v[64:67], v[18:33]
	global_load_lds_dwordx4 v[34:35], off
	v_lshl_add_u64 v[34:35], v[42:43], 0, s[30:31]
	s_mov_b32 m0, s46
	s_nop 0
	global_load_lds_dwordx4 v[34:35], off
	v_lshl_add_u64 v[34:35], v[44:45], 0, s[30:31]
	s_mov_b32 m0, s47
	s_nop 0
	global_load_lds_dwordx4 v[34:35], off
	ds_read_b128 v[34:37], v0
	ds_read_b128 v[38:41], v50 offset:16384
	ds_read_b128 v[42:45], v50 offset:20480
	s_waitcnt lgkmcnt(0)
	v_mfma_f32_32x32x16_bf16 v[2:17], v[34:37], v[38:41], v[2:17]
	v_mfma_f32_32x32x16_bf16 v[18:33], v[34:37], v[42:45], v[18:33]
	ds_read_b128 v[34:37], v48
	ds_read_b128 v[38:41], v49 offset:16384
	ds_read_b128 v[42:45], v49 offset:20480
	s_waitcnt lgkmcnt(1)
	v_mfma_f32_32x32x16_bf16 v[2:17], v[34:37], v[38:41], v[2:17]
	s_waitcnt lgkmcnt(0)
	v_mfma_f32_32x32x16_bf16 v[18:33], v[34:37], v[42:45], v[18:33]
	ds_read_b128 v[34:37], v52
	ds_read_b128 v[38:41], v51 offset:16384
	ds_read_b128 v[42:45], v51 offset:20480
	s_waitcnt lgkmcnt(1)
	v_mfma_f32_32x32x16_bf16 v[2:17], v[34:37], v[38:41], v[2:17]
	s_waitcnt lgkmcnt(0)
	v_mfma_f32_32x32x16_bf16 v[18:33], v[34:37], v[42:45], v[18:33]
	ds_read_b128 v[34:37], v54
	ds_read_b128 v[38:41], v53 offset:16384
	ds_read_b128 v[42:45], v53 offset:20480
	s_waitcnt vmcnt(0)
	s_waitcnt lgkmcnt(0)
	s_barrier
	v_mfma_f32_32x32x16_bf16 v[2:17], v[34:37], v[38:41], v[2:17]
	v_mfma_f32_32x32x16_bf16 v[18:33], v[34:37], v[42:45], v[18:33]
	ds_read_b128 v[34:37], v50 offset:53248
	ds_read_b128 v[38:41], v50 offset:49152
	ds_read_b128 v[42:45], v0 offset:32768
	v_mov_b32_e32 v0, v1
	s_waitcnt lgkmcnt(0)
	v_mfma_f32_32x32x16_bf16 v[2:17], v[42:45], v[38:41], v[2:17]
	v_mfma_f32_32x32x16_bf16 v[18:33], v[42:45], v[34:37], v[18:33]
	ds_read_b128 v[34:37], v48 offset:32768
	ds_read_b128 v[38:41], v49 offset:49152
	ds_read_b128 v[42:45], v49 offset:53248
	s_waitcnt lgkmcnt(1)
	v_mfma_f32_32x32x16_bf16 v[2:17], v[34:37], v[38:41], v[2:17]
	s_waitcnt lgkmcnt(0)
	v_mfma_f32_32x32x16_bf16 v[18:33], v[34:37], v[42:45], v[18:33]
	ds_read_b128 v[34:37], v52 offset:32768
	ds_read_b128 v[38:41], v51 offset:49152
	ds_read_b128 v[42:45], v51 offset:53248
	s_waitcnt lgkmcnt(1)
	v_mfma_f32_32x32x16_bf16 v[2:17], v[34:37], v[38:41], v[2:17]
	s_waitcnt lgkmcnt(0)
	v_mfma_f32_32x32x16_bf16 v[18:33], v[34:37], v[42:45], v[18:33]
	ds_read_b128 v[34:37], v54 offset:32768
	ds_read_b128 v[38:41], v53 offset:49152
	ds_read_b128 v[42:45], v53 offset:53248
	s_waitcnt vmcnt(0)
	s_waitcnt lgkmcnt(0)
	s_barrier
; #define GAS __attribute__((address_space(1)))
; DI int opaque0() { int z = 0; asm volatile("" : "+v"(z)); return z; }
; template <int AI>
; DI void gu_tile(char* wsb, int sub, int m0, int n0, char* lds) {
;     ...
;   const int m0e = m0 + opaque0();
;   const int hc = (n0 >> 1) + wb * 32 + r;
;   GAS u16* HIDu = uptr(HID);
;   const unsigned ib = (unsigned)((m0e + wa * 32 * AI + 4 * h) * 2816 + hc);
; #pragma unroll
;   for (int ai = 0; ai < AI; ++ai)
; #pragma unroll
;     for (int reg = 0; reg < 16; ++reg) {
;       float g = acc[ai][0][reg], u = acc[ai][1][reg];
;       float v = g * __builtin_amdgcn_rcpf(1.f + __expf(-g)) * u;
;       HIDu[ib + (unsigned)((ai * 32 + (reg & 3) + 8 * (reg >> 2)) * 2816)] = f2bf(v);
;       if ((reg & 7) == 7) __builtin_amdgcn_sched_barrier(0);
;     }
; DI void phase_gu(const Params& p, char* wsb, int sub, int mrows, char* lds) {
;     ...
;   for (int rnd = 0; next_tile(rnd, 128, 44, mt, nt); ++rnd) gu_tile<2>(wsb, sub, mt * 128, nt * 128, lds);
;   if (mrows > TL)
;     for (int rnd = 0; next_tile(rnd, 32, 44, mt, nt); ++rnd) gu_tile<1>(wsb, sub, TL + mt * 64, nt * 128, lds);
	v_mfma_f32_32x32x16_bf16 v[2:17], v[34:37], v[38:41], v[2:17]
	v_mfma_f32_32x32x16_bf16 v[18:33], v[34:37], v[42:45], v[18:33]
	v_lshrrev_b32_e32 v36, 3, v46
	v_lshrrev_b32_e32 v34, 1, v47
	v_lshrrev_b32_e32 v35, 2, v47
	v_and_b32_e32 v36, 4, v36
	v_and_b32_e32 v34, 32, v34
	v_and_or_b32 v35, v35, s18, v36
	v_add3_u32 v35, v35, s17, v0
	v_or3_b32 v0, v34, v55, s8
	s_nop 2
	v_mul_f32_e32 v34, 0xbfb8aa3b, v2
	v_exp_f32_e32 v34, v34
	s_nop 0
	v_add_f32_e32 v34, 1.0, v34
	v_rcp_f32_e32 v34, v34
	s_nop 0
	v_mul_f32_e32 v2, v2, v34
	v_mad_u64_u32 v[34:35], s[8:9], v35, s9, v[0:1]
	v_mul_f32_e32 v0, 0xbfb8aa3b, v3
	v_exp_f32_e32 v0, v0
	v_mul_f32_e32 v2, v18, v2
	v_mov_b32_e32 v35, v1
	v_cvt_pk_bf16_f32 v2, v2, s0
	v_add_f32_e32 v0, 1.0, v0
	v_rcp_f32_e32 v0, v0
	v_lshl_add_u64 v[36:37], v[34:35], 1, s[6:7]
	global_store_short v[36:37], v2, off
	v_mul_f32_e32 v0, v3, v0
	v_mul_f32_e32 v0, v19, v0
	v_cvt_pk_bf16_f32 v18, v0, s0
	v_add_u32_e32 v0, 0xb00, v34
	v_lshl_add_u64 v[2:3], v[0:1], 1, s[6:7]
	v_mul_f32_e32 v0, 0xbfb8aa3b, v4
	v_exp_f32_e32 v0, v0
	global_store_short v[2:3], v18, off
	v_add_f32_e32 v0, 1.0, v0
	v_rcp_f32_e32 v0, v0
	s_nop 0
	v_mul_f32_e32 v0, v4, v0
	v_mul_f32_e32 v0, v20, v0
	v_cvt_pk_bf16_f32 v4, v0, s0
	v_add_u32_e32 v0, 0x1600, v34
	v_lshl_add_u64 v[2:3], v[0:1], 1, s[6:7]
	v_mul_f32_e32 v0, 0xbfb8aa3b, v5
	v_exp_f32_e32 v0, v0
	global_store_short v[2:3], v4, off
	v_add_f32_e32 v0, 1.0, v0
	v_rcp_f32_e32 v0, v0
	s_nop 0
	v_mul_f32_e32 v0, v5, v0
	v_mul_f32_e32 v0, v21, v0
	v_cvt_pk_bf16_f32 v4, v0, s0
	v_add_u32_e32 v0, 0x2100, v34
	v_lshl_add_u64 v[2:3], v[0:1], 1, s[6:7]
	v_mul_f32_e32 v0, 0xbfb8aa3b, v6
	v_exp_f32_e32 v0, v0
	global_store_short v[2:3], v4, off
	v_add_f32_e32 v0, 1.0, v0
	v_rcp_f32_e32 v0, v0
	s_nop 0
	v_mul_f32_e32 v0, v6, v0
	v_mul_f32_e32 v0, v22, v0
	v_cvt_pk_bf16_f32 v4, v0, s0
	v_add_u32_e32 v0, 0x5800, v34
	v_lshl_add_u64 v[2:3], v[0:1], 1, s[6:7]
	v_mul_f32_e32 v0, 0xbfb8aa3b, v7
	v_exp_f32_e32 v0, v0
	global_store_short v[2:3], v4, off
	v_add_f32_e32 v0, 1.0, v0
	v_rcp_f32_e32 v0, v0
	s_nop 0
	v_mul_f32_e32 v0, v7, v0
	v_mul_f32_e32 v0, v23, v0
	v_cvt_pk_bf16_f32 v4, v0, s0
	v_add_u32_e32 v0, 0x6300, v34
	v_lshl_add_u64 v[2:3], v[0:1], 1, s[6:7]
	v_mul_f32_e32 v0, 0xbfb8aa3b, v8
	v_exp_f32_e32 v0, v0
	global_store_short v[2:3], v4, off
	v_add_f32_e32 v0, 1.0, v0
	v_rcp_f32_e32 v0, v0
	s_nop 0
	v_mul_f32_e32 v0, v8, v0
	v_mul_f32_e32 v0, v24, v0
	v_cvt_pk_bf16_f32 v4, v0, s0
	v_add_u32_e32 v0, 0x6e00, v34
	v_lshl_add_u64 v[2:3], v[0:1], 1, s[6:7]
	v_mul_f32_e32 v0, 0xbfb8aa3b, v9
	v_exp_f32_e32 v0, v0
	global_store_short v[2:3], v4, off
	v_add_f32_e32 v0, 1.0, v0
	v_rcp_f32_e32 v0, v0
	s_nop 0
	v_mul_f32_e32 v0, v9, v0
	v_mul_f32_e32 v0, v25, v0
	v_cvt_pk_bf16_f32 v4, v0, s0
	v_add_u32_e32 v0, 0x7900, v34
	v_lshl_add_u64 v[2:3], v[0:1], 1, s[6:7]
	global_store_short v[2:3], v4, off
	v_mul_f32_e32 v0, 0xbfb8aa3b, v10
	v_exp_f32_e32 v0, v0
	s_nop 0
	v_add_f32_e32 v0, 1.0, v0
	v_rcp_f32_e32 v0, v0
	s_nop 0
	v_mul_f32_e32 v0, v10, v0
	v_mul_f32_e32 v0, v26, v0
	v_cvt_pk_bf16_f32 v4, v0, s0
	v_add_u32_e32 v0, 0xb000, v34
	v_lshl_add_u64 v[2:3], v[0:1], 1, s[6:7]
	v_mul_f32_e32 v0, 0xbfb8aa3b, v11
	v_exp_f32_e32 v0, v0
	global_store_short v[2:3], v4, off
	v_add_f32_e32 v0, 1.0, v0
	v_rcp_f32_e32 v0, v0
	s_nop 0
	v_mul_f32_e32 v0, v11, v0
	v_mul_f32_e32 v0, v27, v0
	v_cvt_pk_bf16_f32 v4, v0, s0
	v_add_u32_e32 v0, 0xbb00, v34
	v_lshl_add_u64 v[2:3], v[0:1], 1, s[6:7]
	v_mul_f32_e32 v0, 0xbfb8aa3b, v12
	v_exp_f32_e32 v0, v0
	global_store_short v[2:3], v4, off
	v_add_f32_e32 v0, 1.0, v0
	v_rcp_f32_e32 v0, v0
	s_nop 0
	v_mul_f32_e32 v0, v12, v0
	v_mul_f32_e32 v0, v28, v0
	v_cvt_pk_bf16_f32 v4, v0, s0
	v_add_u32_e32 v0, 0xc600, v34
	v_lshl_add_u64 v[2:3], v[0:1], 1, s[6:7]
	v_mul_f32_e32 v0, 0xbfb8aa3b, v13
	v_exp_f32_e32 v0, v0
	global_store_short v[2:3], v4, off
	v_add_f32_e32 v0, 1.0, v0
	v_rcp_f32_e32 v0, v0
	s_nop 0
	v_mul_f32_e32 v0, v13, v0
	v_mul_f32_e32 v0, v29, v0
	v_cvt_pk_bf16_f32 v4, v0, s0
	v_add_u32_e32 v0, 0xd100, v34
	v_lshl_add_u64 v[2:3], v[0:1], 1, s[6:7]
	v_mul_f32_e32 v0, 0xbfb8aa3b, v14
	v_exp_f32_e32 v0, v0
	global_store_short v[2:3], v4, off
	v_add_f32_e32 v0, 1.0, v0
	v_rcp_f32_e32 v0, v0
	s_nop 0
	v_mul_f32_e32 v0, v14, v0
	v_mul_f32_e32 v0, v30, v0
	v_cvt_pk_bf16_f32 v4, v0, s0
	v_add_u32_e32 v0, 0x10800, v34
	v_lshl_add_u64 v[2:3], v[0:1], 1, s[6:7]
	v_mul_f32_e32 v0, 0xbfb8aa3b, v15
	v_exp_f32_e32 v0, v0
	global_store_short v[2:3], v4, off
	v_add_f32_e32 v0, 1.0, v0
	v_rcp_f32_e32 v0, v0
	s_nop 0
	v_mul_f32_e32 v0, v15, v0
	v_mul_f32_e32 v0, v31, v0
	v_cvt_pk_bf16_f32 v4, v0, s0
	v_add_u32_e32 v0, 0x11300, v34
	v_lshl_add_u64 v[2:3], v[0:1], 1, s[6:7]
	v_mul_f32_e32 v0, 0xbfb8aa3b, v16
	v_exp_f32_e32 v0, v0
	global_store_short v[2:3], v4, off
	v_add_f32_e32 v0, 1.0, v0
	v_rcp_f32_e32 v0, v0
	s_nop 0
	v_mul_f32_e32 v0, v16, v0
	v_mul_f32_e32 v0, v32, v0
	v_cvt_pk_bf16_f32 v4, v0, s0
	v_add_u32_e32 v0, 0x11e00, v34
	v_lshl_add_u64 v[2:3], v[0:1], 1, s[6:7]
	v_mul_f32_e32 v0, 0xbfb8aa3b, v17
	v_exp_f32_e32 v0, v0
	global_store_short v[2:3], v4, off
	v_add_f32_e32 v0, 1.0, v0
	v_rcp_f32_e32 v0, v0
	s_nop 0
	v_mul_f32_e32 v0, v17, v0
	v_mul_f32_e32 v0, v33, v0
	v_cvt_pk_bf16_f32 v4, v0, s0
	v_add_u32_e32 v0, 0x12900, v34
	v_lshl_add_u64 v[2:3], v[0:1], 1, s[6:7]
	global_store_short v[2:3], v4, off
	v_readlane_b32 s8, v243, 9
	s_add_i32 s16, s16, s8
	v_readlane_b32 s8, v243, 11
	s_add_i32 s15, s15, s8
	s_add_i32 s14, s14, s48
	s_cmpk_gt_u32 s14, 0x57f
	s_cbranch_scc0 .LBB0_423
.Lgc1_exit:
	v_readlane_b32 s16, v243, 45
	v_readlane_b32 s28, v243, 47
	v_readlane_b32 s17, v243, 46
	v_readlane_b32 s29, v243, 48
	v_readlane_b32 s47, v243, 51

; template <int AI, int BI>
; DI void gemm_tile(const u16* __restrict__ A, int lda, const u16* __restrict__ B, int ldb, int nk, bool swap,
;                   f32x16 (&acc)[AI][BI], char* lds) {
;     ...
;   const int wa = wid >> 1, wb = wid & 1, r = lane & 31, h = lane >> 5, sw = (r >> 1) & 7;
;   const int offA = (swap ? 16384 : 0) + (wa * 32 * AI + r) * 128;
;   const int offB = (swap ? 0 : 16384) + (wb * 32 * BI + r) * 128;
; DI void phase_gu(const Params& p, char* wsb, int sub, int mrows, char* lds) {
;   int mt, nt;
;   for (int rnd = 0; next_tile(rnd, 128, 44, mt, nt); ++rnd) gu_tile<2>(wsb, sub, mt * 128, nt * 128, lds);
;   if (mrows > TL)
;     for (int rnd = 0; next_tile(rnd, 32, 44, mt, nt); ++rnd) gu_tile<1>(wsb, sub, TL + mt * 64, nt * 128, lds);
.LBB0_1208:
	v_readlane_b32 s6, v244, 59
	v_readlane_b32 s10, v242, 9
	v_readlane_b32 s7, v244, 60
	v_readlane_b32 s11, v242, 10
	s_or_b64 s[6:7], s[10:11], s[6:7]
	s_and_b64 vcc, exec, s[6:7]
	s_cbranch_vccnz .LBB0_1212
	s_add_u32 s10, s8, 0x77b7000
	s_addc_u32 s11, s9, 0
	s_add_u32 s12, s8, 0x1d537000
	s_addc_u32 s13, s9, 0
	s_add_u32 s6, s8, 0x9bb7000
	s_addc_u32 s7, s9, 0
	v_readlane_b32 s14, v243, 18
	v_readlane_b32 s15, v243, 10
	v_readlane_b32 s16, v243, 8
	v_readlane_b32 s48, v243, 7
	v_readlane_b32 s49, v243, 9
	v_readlane_b32 s50, v243, 11
	s_movk_i32 s51, 0xb00
	s_mov_b32 s52, 0x1ffffe0
	s_mov_b32 s53, 0xffffe0
	s_mov_b64 s[56:57], 0x200
	s_mov_b64 s[64:65], 0x80
	s_mov_b64 s[66:67], 0x180
	s_mov_b64 s[68:69], 0x280
	s_mov_b64 s[70:71], 0x300
	s_mov_b64 s[72:73], 0x380
	s_mov_b64 s[74:75], 0x400
	s_mov_b64 s[76:77], 0x480
	s_mov_b64 s[80:81], 0x500
	s_mov_b64 s[82:83], 0x580
	s_mov_b64 s[84:85], 0x600
	s_waitcnt vmcnt(0)
	s_cmpk_lg_u32 s92, 0x200
	s_cbranch_scc1 .LBB0_1210
	v_and_b32_e32 v70, 31, v178
	v_bfe_u32 v71, v178, 5, 1
	v_bfe_u32 v72, v178, 2, 2
	v_xor_b32_e32 v71, v71, v72
	v_lshlrev_b32_e32 v71, 4, v71
	v_bfe_u32 v72, v178, 7, 1
	v_lshl_add_u32 v72, v72, 5, v70
	v_lshl_add_u32 v58, v72, 6, v71
	v_xor_b32_e32 v59, 32, v58
	v_bfe_u32 v72, v178, 6, 1
	v_lshl_add_u32 v72, v72, 6, v70
	v_lshl_add_u32 v60, v72, 6, v71
	v_add_u32_e32 v60, 0x1000, v60
	v_xor_b32_e32 v61, 32, v60
	v_bfe_u32 v71, v178, 7, 1
	v_lshlrev_b32_e32 v71, 5, v71
	v_bfe_u32 v72, v178, 5, 1
	v_lshl_add_u32 v71, v72, 2, v71
	v_mul_u32_u24_e32 v71, 0xb00, v71
	v_bfe_u32 v72, v178, 6, 1
	v_lshl_add_u32 v72, v72, 5, v70
	v_add_u32_e32 v71, v71, v72
	v_lshlrev_b32_e32 v64, 1, v71
	v_lshrrev_b32_e32 v70, 2, v178
	v_bfe_u32 v71, v178, 4, 2
	v_and_b32_e32 v72, 3, v178
	v_xor_b32_e32 v71, v71, v72
	v_lshlrev_b32_e32 v71, 4, v71
	v_lshl_add_u32 v62, v70, 11, v71
	v_add_u32_e32 v63, 0x20000, v62
	v_lshrrev_b32_e32 v70, 6, v178
	s_nop 1
	v_readfirstlane_b32 s17, v70
	s_lshl_b32 s17, s17, 10
	s_mov_b32 s36, s14

; #define MFMA(a, b, c) __builtin_amdgcn_mfma_f32_32x32x16_bf16((a), (b), (c), 0, 0, 0)
; #define TIDX opaque_tid()
; template <int AI, int BI>
; DI void gemm_tile(const u16* __restrict__ A, int lda, const u16* __restrict__ B, int ldb, int nk, bool swap,
;                   f32x16 (&acc)[AI][BI], char* lds) {
;   const int tid = TIDX, lane = tid & 63, wid = tid >> 6;
;   gemm_stage<AI, BI>(A, lda, B, ldb, lds, tid);
;   asm volatile("s_waitcnt vmcnt(0)" ::: "memory");
;   __syncthreads();
;   const int wa = wid >> 1, wb = wid & 1, r = lane & 31, h = lane >> 5, sw = (r >> 1) & 7;
;   const int offA = (swap ? 16384 : 0) + (wa * 32 * AI + r) * 128;
;   const int offB = (swap ? 0 : 16384) + (wb * 32 * BI + r) * 128;
;   for (int kt = 0; kt < nk; ++kt) {
;     const char* cur = lds + (kt & 1) * 32768;
;     if (kt + 1 < nk) gemm_stage<AI, BI>(A + (kt + 1) * 64, lda, B + (kt + 1) * 64, ldb, lds + ((kt + 1) & 1) * 32768, tid);
; #pragma unroll
;     for (int ks = 0; ks < 4; ++ks) {
;       const int co = ((ks * 2 + h) ^ sw) << 4;
;       s16x8 fa[AI], fb[BI];
; #pragma unroll
;       for (int i = 0; i < AI; ++i) fa[i] = *(const s16x8*)(cur + offA + i * 4096 + co);
; #pragma unroll
;       for (int i = 0; i < BI; ++i) fb[i] = *(const s16x8*)(cur + offB + i * 4096 + co);
; #pragma unroll
;       for (int i = 0; i < AI; ++i)
; #pragma unroll
;         for (int j = 0; j < BI; ++j) acc[i][j] = MFMA(fa[i], fb[j], acc[i][j]);
;     }
;     asm volatile("s_waitcnt vmcnt(0)" ::: "memory");
;     __syncthreads();
;   }
; DI bool next_tile(int rnd, int MT, int NT, int& mt, int& nt) {
;   const int G8 = gridDim.x >> 3, x = blockIdx.x & 7, slot = blockIdx.x >> 3;
;   const int T = (rnd * 8 + x) * G8 + slot;
;   if (T >= MT * NT) return false;
;   const int band = T / (NT * 8), rem = T - band * NT * 8;
;   nt = rem >> 3; mt = band * 8 + (rem & 7);
.LBB0_1210:
	s_and_b32 s8, s14, 0xffff
	s_mul_hi_u32 s9, s8, 0xba2e8c
	s_mul_i32 s8, s8, 0xba2f
	s_lshr_b32 s8, s8, 24
	s_lshl_b32 s8, s8, 9
	s_and_b32 s17, s16, 0x1c0
	s_mulk_i32 s9, 0x1600
	s_or_b32 s17, s8, s17
	s_sub_i32 s9, s15, s9
	s_addk_i32 s17, 0x4000
	s_and_b32 s8, s9, 0xffffff80
	v_mov_b32_e32 v46, v178
	v_mov_b32_e32 v47, v178
	s_lshl_b32 s9, s17, 11
	v_mov_b32_e32 v8, v178
	s_add_u32 s28, s10, s9
	s_addc_u32 s29, s11, 0
	v_lshrrev_b32_e32 v0, 4, v8
	s_ashr_i32 s9, s8, 31
	v_xor_b32_e32 v0, v0, v8
	v_add_u32_e32 v9, 0x100, v8
	s_lshl_b64 s[34:35], s[8:9], 11
	v_lshlrev_b32_e32 v0, 4, v0
	v_ashrrev_i32_e32 v4, 3, v8
	v_ashrrev_i32_e32 v6, 3, v9
	s_add_u32 s34, s12, s34
	v_and_b32_e32 v0, 0x70, v0
	v_ashrrev_i32_e32 v5, 31, v4
	v_ashrrev_i32_e32 v7, 31, v6
	s_addc_u32 s35, s13, s35
	v_lshl_add_u64 v[2:3], s[28:29], 0, v[0:1]
	v_lshlrev_b64 v[4:5], 11, v[4:5]
	v_lshlrev_b64 v[6:7], 11, v[6:7]
	v_lshl_add_u64 v[34:35], v[2:3], 0, v[4:5]
	v_lshl_add_u64 v[36:37], v[2:3], 0, v[6:7]
	v_lshl_add_u64 v[2:3], s[34:35], 0, v[0:1]
	v_add_u32_e32 v0, 0x200, v8
	v_lshl_add_u64 v[40:41], v[2:3], 0, v[4:5]
	v_ashrrev_i32_e32 v4, 3, v0
	v_ashrrev_i32_e32 v5, 31, v4
	v_lshl_add_u64 v[38:39], v[2:3], 0, v[6:7]
	v_lshlrev_b64 v[4:5], 11, v[4:5]
	v_add_u32_e32 v6, 0x300, v8
	v_lshl_add_u64 v[42:43], v[2:3], 0, v[4:5]
	v_ashrrev_i32_e32 v4, 3, v6
	v_ashrrev_i32_e32 v5, 31, v4
	v_lshlrev_b32_e32 v55, 4, v8
	v_lshlrev_b64 v[4:5], 11, v[4:5]
	v_readfirstlane_b32 s9, v55
	v_lshlrev_b32_e32 v56, 4, v9
	v_lshl_add_u64 v[44:45], v[2:3], 0, v[4:5]
	v_and_b32_e32 v2, 31, v8
	v_lshrrev_b32_e32 v7, 2, v8
	s_mov_b32 m0, s9
	v_readfirstlane_b32 s18, v56
	v_add_u32_e32 v57, 0x4000, v55
	v_and_or_b32 v2, v7, s52, v2
	global_load_lds_dwordx4 v[34:35], off
	s_mov_b32 m0, s18
	v_readfirstlane_b32 s28, v57
	v_add_u32_e32 v59, 0x4000, v56
	v_lshlrev_b32_e32 v0, 4, v0
	v_lshlrev_b32_e32 v4, 4, v6
	v_lshrrev_b32_e32 v3, 5, v8
	v_bfe_u32 v6, v8, 1, 3
	v_lshlrev_b32_e32 v53, 7, v2
	v_lshlrev_b32_e32 v2, 7, v8
	global_load_lds_dwordx4 v[36:37], off
	s_mov_b32 m0, s28
	v_readfirstlane_b32 s29, v59
	v_add_u32_e32 v65, 0x4000, v0
	v_bfe_u32 v5, v8, 5, 1
	v_and_b32_e32 v67, 0x2f80, v2
	v_bitop3_b32 v2, v3, v6, 1 bitop3:0x6c
	global_load_lds_dwordx4 v[40:41], off
	s_mov_b32 m0, s29
	v_readfirstlane_b32 s34, v65
	v_add_u32_e32 v66, 0x4000, v4
	v_lshlrev_b32_e32 v7, 4, v2
	v_bitop3_b32 v2, v5, v6, 2 bitop3:0x36
	global_load_lds_dwordx4 v[38:39], off
	s_mov_b32 m0, s34
	v_readfirstlane_b32 s41, v66
	v_lshlrev_b32_e32 v49, 4, v2
	v_bitop3_b32 v2, v5, v6, 4 bitop3:0x36
	v_add_u32_e32 v64, 0x8000, v55
	global_load_lds_dwordx4 v[42:43], off
	s_mov_b32 m0, s41
	v_lshlrev_b32_e32 v51, 4, v2
	v_bitop3_b32 v2, v5, v6, 6 bitop3:0x36
	v_readfirstlane_b32 s35, v64
	v_add_u32_e32 v61, 0x8000, v56
	global_load_lds_dwordx4 v[44:45], off
	v_lshlrev_b32_e32 v80, 4, v2
	v_lshl_add_u64 v[2:3], v[34:35], 0, s[64:65]
	s_mov_b32 m0, s35
	v_readfirstlane_b32 s36, v61
	v_add_u32_e32 v58, 0xc000, v55
	s_waitcnt vmcnt(0)
	s_waitcnt vmcnt(0) lgkmcnt(0)
	s_barrier
	global_load_lds_dwordx4 v[2:3], off
	v_lshl_add_u64 v[2:3], v[36:37], 0, s[64:65]
	s_mov_b32 m0, s36
	v_readfirstlane_b32 s37, v58
	v_add_u32_e32 v60, 0xc000, v56
	global_load_lds_dwordx4 v[2:3], off
	v_lshl_add_u64 v[2:3], v[40:41], 0, s[64:65]
	s_mov_b32 m0, s37
	v_readfirstlane_b32 s40, v60
	v_add_u32_e32 v62, 0xc000, v0
	global_load_lds_dwordx4 v[2:3], off
	v_lshl_add_u64 v[2:3], v[38:39], 0, s[64:65]
	s_mov_b32 m0, s40
	v_readfirstlane_b32 s46, v62
	v_add_u32_e32 v63, 0xc000, v4
	global_load_lds_dwordx4 v[2:3], off
	v_lshl_add_u64 v[2:3], v[42:43], 0, s[64:65]
	s_mov_b32 m0, s46
	v_readfirstlane_b32 s47, v63
	global_load_lds_dwordx4 v[2:3], off
	v_lshl_add_u64 v[2:3], v[44:45], 0, s[64:65]
	s_mov_b32 m0, s47
	v_or_b32_e32 v0, v53, v7
	global_load_lds_dwordx4 v[2:3], off
	ds_read_b128 v[18:21], v0
	v_or_b32_e32 v50, v67, v7
	ds_read_b128 v[2:5], v50 offset:16384
	ds_read_b128 v[22:25], v50 offset:20480
	v_or_b32_e32 v48, v53, v49
	ds_read_b128 v[68:71], v48
	s_waitcnt lgkmcnt(0)
	v_mfma_f32_32x32x16_bf16 v[2:17], v[18:21], v[2:5], 0
	v_or_b32_e32 v49, v67, v49
	ds_read_b128 v[72:75], v49 offset:16384
	ds_read_b128 v[76:79], v49 offset:20480
	v_or_b32_e32 v52, v53, v51
	v_or_b32_e32 v51, v67, v51
	v_or_b32_e32 v54, v53, v80
	v_or_b32_e32 v53, v67, v80
	s_mov_b32 m0, s9
	v_mfma_f32_32x32x16_bf16 v[18:33], v[18:21], v[22:25], 0
	s_ashr_i32 s8, s8, 1
	s_waitcnt lgkmcnt(1)
	v_mfma_f32_32x32x16_bf16 v[2:17], v[68:71], v[72:75], v[2:17]
	s_waitcnt lgkmcnt(0)
	v_mfma_f32_32x32x16_bf16 v[18:33], v[68:71], v[76:79], v[18:33]
	ds_read_b128 v[68:71], v52
	ds_read_b128 v[72:75], v51 offset:16384
	ds_read_b128 v[76:79], v51 offset:20480
	s_waitcnt lgkmcnt(1)
	v_mfma_f32_32x32x16_bf16 v[2:17], v[68:71], v[72:75], v[2:17]
	s_waitcnt lgkmcnt(0)
	v_mfma_f32_32x32x16_bf16 v[18:33], v[68:71], v[76:79], v[18:33]
	ds_read_b128 v[68:71], v54
	ds_read_b128 v[72:75], v53 offset:16384
	ds_read_b128 v[76:79], v53 offset:20480
	s_waitcnt vmcnt(0)
	s_waitcnt lgkmcnt(0)
	s_barrier
; #define MFMA(a, b, c) __builtin_amdgcn_mfma_f32_32x32x16_bf16((a), (b), (c), 0, 0, 0)
; template <int AI, int BI>
; DI void gemm_tile(const u16* __restrict__ A, int lda, const u16* __restrict__ B, int ldb, int nk, bool swap,
;                   f32x16 (&acc)[AI][BI], char* lds) {
;     ...
;   for (int kt = 0; kt < nk; ++kt) {
;     const char* cur = lds + (kt & 1) * 32768;
;     if (kt + 1 < nk) gemm_stage<AI, BI>(A + (kt + 1) * 64, lda, B + (kt + 1) * 64, ldb, lds + ((kt + 1) & 1) * 32768, tid);
; #pragma unroll
;     for (int ks = 0; ks < 4; ++ks) {
;       const int co = ((ks * 2 + h) ^ sw) << 4;
;       s16x8 fa[AI], fb[BI];
; #pragma unroll
;       for (int i = 0; i < AI; ++i) fa[i] = *(const s16x8*)(cur + offA + i * 4096 + co);
; #pragma unroll
;       for (int i = 0; i < BI; ++i) fb[i] = *(const s16x8*)(cur + offB + i * 4096 + co);
; #pragma unroll
;       for (int i = 0; i < AI; ++i)
; #pragma unroll
;         for (int j = 0; j < BI; ++j) acc[i][j] = MFMA(fa[i], fb[j], acc[i][j]);
;     }
;     asm volatile("s_waitcnt vmcnt(0)" ::: "memory");
;     __syncthreads();
;   }
	v_mfma_f32_32x32x16_bf16 v[2:17], v[68:71], v[72:75], v[2:17]
	v_mfma_f32_32x32x16_bf16 v[18:33], v[68:71], v[76:79], v[18:33]
	v_lshl_add_u64 v[68:69], v[34:35], 0, s[4:5]
	global_load_lds_dwordx4 v[68:69], off
	v_lshl_add_u64 v[68:69], v[36:37], 0, s[4:5]
	s_mov_b32 m0, s18
	s_nop 0
	global_load_lds_dwordx4 v[68:69], off
	v_lshl_add_u64 v[68:69], v[40:41], 0, s[4:5]
	s_mov_b32 m0, s28
	s_nop 0
	global_load_lds_dwordx4 v[68:69], off
	v_lshl_add_u64 v[68:69], v[38:39], 0, s[4:5]
	s_mov_b32 m0, s29
	s_nop 0
	global_load_lds_dwordx4 v[68:69], off
	v_lshl_add_u64 v[68:69], v[42:43], 0, s[4:5]
	s_mov_b32 m0, s34
	s_nop 0
	global_load_lds_dwordx4 v[68:69], off
	v_lshl_add_u64 v[68:69], v[44:45], 0, s[4:5]
	s_mov_b32 m0, s41
	s_nop 0
	global_load_lds_dwordx4 v[68:69], off
	ds_read_b128 v[68:71], v0 offset:32768
	ds_read_b128 v[72:75], v50 offset:49152
	ds_read_b128 v[76:79], v50 offset:53248
	s_waitcnt lgkmcnt(0)
	v_mfma_f32_32x32x16_bf16 v[2:17], v[68:71], v[72:75], v[2:17]
	s_mov_b32 m0, s35
	v_mfma_f32_32x32x16_bf16 v[18:33], v[68:71], v[76:79], v[18:33]
	ds_read_b128 v[68:71], v48 offset:32768
	ds_read_b128 v[72:75], v49 offset:49152
	ds_read_b128 v[76:79], v49 offset:53248
	s_waitcnt lgkmcnt(1)
	v_mfma_f32_32x32x16_bf16 v[2:17], v[68:71], v[72:75], v[2:17]
	s_waitcnt lgkmcnt(0)
	v_mfma_f32_32x32x16_bf16 v[18:33], v[68:71], v[76:79], v[18:33]
	ds_read_b128 v[68:71], v52 offset:32768
	ds_read_b128 v[72:75], v51 offset:49152
	ds_read_b128 v[76:79], v51 offset:53248
	s_waitcnt lgkmcnt(1)
	v_mfma_f32_32x32x16_bf16 v[2:17], v[68:71], v[72:75], v[2:17]
	s_waitcnt lgkmcnt(0)
	v_mfma_f32_32x32x16_bf16 v[18:33], v[68:71], v[76:79], v[18:33]
	ds_read_b128 v[68:71], v54 offset:32768
	ds_read_b128 v[72:75], v53 offset:49152
	ds_read_b128 v[76:79], v53 offset:53248
	s_waitcnt vmcnt(0)
	s_waitcnt lgkmcnt(0)
	s_barrier
	v_mfma_f32_32x32x16_bf16 v[2:17], v[68:71], v[72:75], v[2:17]
	v_mfma_f32_32x32x16_bf16 v[18:33], v[68:71], v[76:79], v[18:33]
	v_lshl_add_u64 v[68:69], v[34:35], 0, s[66:67]
	global_load_lds_dwordx4 v[68:69], off
	v_lshl_add_u64 v[68:69], v[36:37], 0, s[66:67]
	s_mov_b32 m0, s36
	s_nop 0
	global_load_lds_dwordx4 v[68:69], off
	v_lshl_add_u64 v[68:69], v[40:41], 0, s[66:67]
	s_mov_b32 m0, s37
	s_nop 0
	global_load_lds_dwordx4 v[68:69], off
	v_lshl_add_u64 v[68:69], v[38:39], 0, s[66:67]
	s_mov_b32 m0, s40
	s_nop 0
	global_load_lds_dwordx4 v[68:69], off
	v_lshl_add_u64 v[68:69], v[42:43], 0, s[66:67]
	s_mov_b32 m0, s46
	s_nop 0
	global_load_lds_dwordx4 v[68:69], off
	v_lshl_add_u64 v[68:69], v[44:45], 0, s[66:67]
	s_mov_b32 m0, s47
	s_nop 0
	global_load_lds_dwordx4 v[68:69], off
	ds_read_b128 v[68:71], v0
	ds_read_b128 v[72:75], v50 offset:16384
	ds_read_b128 v[76:79], v50 offset:20480
	s_waitcnt lgkmcnt(0)
	v_mfma_f32_32x32x16_bf16 v[2:17], v[68:71], v[72:75], v[2:17]
	s_mov_b32 m0, s9
	v_mfma_f32_32x32x16_bf16 v[18:33], v[68:71], v[76:79], v[18:33]
	ds_read_b128 v[68:71], v48
	ds_read_b128 v[72:75], v49 offset:16384
	ds_read_b128 v[76:79], v49 offset:20480
	s_waitcnt lgkmcnt(1)
	v_mfma_f32_32x32x16_bf16 v[2:17], v[68:71], v[72:75], v[2:17]
	s_waitcnt lgkmcnt(0)
	v_mfma_f32_32x32x16_bf16 v[18:33], v[68:71], v[76:79], v[18:33]
	ds_read_b128 v[68:71], v52
	ds_read_b128 v[72:75], v51 offset:16384
	ds_read_b128 v[76:79], v51 offset:20480
	s_waitcnt lgkmcnt(1)
	v_mfma_f32_32x32x16_bf16 v[2:17], v[68:71], v[72:75], v[2:17]
	s_waitcnt lgkmcnt(0)
	v_mfma_f32_32x32x16_bf16 v[18:33], v[68:71], v[76:79], v[18:33]
	ds_read_b128 v[68:71], v54
	ds_read_b128 v[72:75], v53 offset:16384
	ds_read_b128 v[76:79], v53 offset:20480
	s_waitcnt vmcnt(0)
	s_waitcnt lgkmcnt(0)
	s_barrier
	v_mfma_f32_32x32x16_bf16 v[2:17], v[68:71], v[72:75], v[2:17]
	v_mfma_f32_32x32x16_bf16 v[18:33], v[68:71], v[76:79], v[18:33]
	v_lshl_add_u64 v[68:69], v[34:35], 0, s[56:57]
	global_load_lds_dwordx4 v[68:69], off
	v_lshl_add_u64 v[68:69], v[36:37], 0, s[56:57]
	s_mov_b32 m0, s18
	s_nop 0
	global_load_lds_dwordx4 v[68:69], off
	v_lshl_add_u64 v[68:69], v[40:41], 0, s[56:57]
	s_mov_b32 m0, s28
	s_nop 0
	global_load_lds_dwordx4 v[68:69], off
	v_lshl_add_u64 v[68:69], v[38:39], 0, s[56:57]
	s_mov_b32 m0, s29
	s_nop 0
	global_load_lds_dwordx4 v[68:69], off
	v_lshl_add_u64 v[68:69], v[42:43], 0, s[56:57]
	s_mov_b32 m0, s34
	s_nop 0
	global_load_lds_dwordx4 v[68:69], off
	v_lshl_add_u64 v[68:69], v[44:45], 0, s[56:57]
	s_mov_b32 m0, s41
	s_nop 0
	global_load_lds_dwordx4 v[68:69], off
	ds_read_b128 v[68:71], v0 offset:32768
	ds_read_b128 v[72:75], v50 offset:49152
	ds_read_b128 v[76:79], v50 offset:53248
	s_waitcnt lgkmcnt(0)
	v_mfma_f32_32x32x16_bf16 v[2:17], v[68:71], v[72:75], v[2:17]
	s_mov_b32 m0, s35
	v_mfma_f32_32x32x16_bf16 v[18:33], v[68:71], v[76:79], v[18:33]
	ds_read_b128 v[68:71], v48 offset:32768
	ds_read_b128 v[72:75], v49 offset:49152
	ds_read_b128 v[76:79], v49 offset:53248
	s_waitcnt lgkmcnt(1)
	v_mfma_f32_32x32x16_bf16 v[2:17], v[68:71], v[72:75], v[2:17]
	s_waitcnt lgkmcnt(0)
	v_mfma_f32_32x32x16_bf16 v[18:33], v[68:71], v[76:79], v[18:33]
	ds_read_b128 v[68:71], v52 offset:32768
	ds_read_b128 v[72:75], v51 offset:49152
	ds_read_b128 v[76:79], v51 offset:53248
	s_waitcnt lgkmcnt(1)
	v_mfma_f32_32x32x16_bf16 v[2:17], v[68:71], v[72:75], v[2:17]
	s_waitcnt lgkmcnt(0)
	v_mfma_f32_32x32x16_bf16 v[18:33], v[68:71], v[76:79], v[18:33]
	ds_read_b128 v[68:71], v54 offset:32768
	ds_read_b128 v[72:75], v53 offset:49152
	ds_read_b128 v[76:79], v53 offset:53248
	s_waitcnt vmcnt(0)
	s_waitcnt lgkmcnt(0)
	s_barrier
; #define MFMA(a, b, c) __builtin_amdgcn_mfma_f32_32x32x16_bf16((a), (b), (c), 0, 0, 0)
; template <int AI, int BI>
; DI void gemm_tile(const u16* __restrict__ A, int lda, const u16* __restrict__ B, int ldb, int nk, bool swap,
;                   f32x16 (&acc)[AI][BI], char* lds) {
;     ...
;   for (int kt = 0; kt < nk; ++kt) {
;     const char* cur = lds + (kt & 1) * 32768;
;     if (kt + 1 < nk) gemm_stage<AI, BI>(A + (kt + 1) * 64, lda, B + (kt + 1) * 64, ldb, lds + ((kt + 1) & 1) * 32768, tid);
; #pragma unroll
;     for (int ks = 0; ks < 4; ++ks) {
;       const int co = ((ks * 2 + h) ^ sw) << 4;
;       s16x8 fa[AI], fb[BI];
; #pragma unroll
;       for (int i = 0; i < AI; ++i) fa[i] = *(const s16x8*)(cur + offA + i * 4096 + co);
; #pragma unroll
;       for (int i = 0; i < BI; ++i) fb[i] = *(const s16x8*)(cur + offB + i * 4096 + co);
; #pragma unroll
;       for (int i = 0; i < AI; ++i)
; #pragma unroll
;         for (int j = 0; j < BI; ++j) acc[i][j] = MFMA(fa[i], fb[j], acc[i][j]);
;     }
;     asm volatile("s_waitcnt vmcnt(0)" ::: "memory");
;     __syncthreads();
;   }
	v_mfma_f32_32x32x16_bf16 v[2:17], v[68:71], v[72:75], v[2:17]
	v_mfma_f32_32x32x16_bf16 v[18:33], v[68:71], v[76:79], v[18:33]
	v_lshl_add_u64 v[68:69], v[34:35], 0, s[68:69]
	global_load_lds_dwordx4 v[68:69], off
	v_lshl_add_u64 v[68:69], v[36:37], 0, s[68:69]
	s_mov_b32 m0, s36
	s_nop 0
	global_load_lds_dwordx4 v[68:69], off
	v_lshl_add_u64 v[68:69], v[40:41], 0, s[68:69]
	s_mov_b32 m0, s37
	s_nop 0
	global_load_lds_dwordx4 v[68:69], off
	v_lshl_add_u64 v[68:69], v[38:39], 0, s[68:69]
	s_mov_b32 m0, s40
	s_nop 0
	global_load_lds_dwordx4 v[68:69], off
	v_lshl_add_u64 v[68:69], v[42:43], 0, s[68:69]
	s_mov_b32 m0, s46
	s_nop 0
	global_load_lds_dwordx4 v[68:69], off
	v_lshl_add_u64 v[68:69], v[44:45], 0, s[68:69]
	s_mov_b32 m0, s47
	s_nop 0
	global_load_lds_dwordx4 v[68:69], off
	ds_read_b128 v[68:71], v0
	ds_read_b128 v[72:75], v50 offset:16384
	ds_read_b128 v[76:79], v50 offset:20480
	s_waitcnt lgkmcnt(0)
	v_mfma_f32_32x32x16_bf16 v[2:17], v[68:71], v[72:75], v[2:17]
	s_mov_b32 m0, s9
	v_mfma_f32_32x32x16_bf16 v[18:33], v[68:71], v[76:79], v[18:33]
	ds_read_b128 v[68:71], v48
	ds_read_b128 v[72:75], v49 offset:16384
	ds_read_b128 v[76:79], v49 offset:20480
	s_waitcnt lgkmcnt(1)
	v_mfma_f32_32x32x16_bf16 v[2:17], v[68:71], v[72:75], v[2:17]
	s_waitcnt lgkmcnt(0)
	v_mfma_f32_32x32x16_bf16 v[18:33], v[68:71], v[76:79], v[18:33]
	ds_read_b128 v[68:71], v52
	ds_read_b128 v[72:75], v51 offset:16384
	ds_read_b128 v[76:79], v51 offset:20480
	s_waitcnt lgkmcnt(1)
	v_mfma_f32_32x32x16_bf16 v[2:17], v[68:71], v[72:75], v[2:17]
	s_waitcnt lgkmcnt(0)
	v_mfma_f32_32x32x16_bf16 v[18:33], v[68:71], v[76:79], v[18:33]
	ds_read_b128 v[68:71], v54
	ds_read_b128 v[72:75], v53 offset:16384
	ds_read_b128 v[76:79], v53 offset:20480
	s_waitcnt vmcnt(0)
	s_waitcnt lgkmcnt(0)
	s_barrier
	v_mfma_f32_32x32x16_bf16 v[2:17], v[68:71], v[72:75], v[2:17]
	v_mfma_f32_32x32x16_bf16 v[18:33], v[68:71], v[76:79], v[18:33]
	v_lshl_add_u64 v[68:69], v[34:35], 0, s[70:71]
	global_load_lds_dwordx4 v[68:69], off
	v_lshl_add_u64 v[68:69], v[36:37], 0, s[70:71]
	s_mov_b32 m0, s18
	s_nop 0
	global_load_lds_dwordx4 v[68:69], off
	v_lshl_add_u64 v[68:69], v[40:41], 0, s[70:71]
	s_mov_b32 m0, s28
	s_nop 0
	global_load_lds_dwordx4 v[68:69], off
	v_lshl_add_u64 v[68:69], v[38:39], 0, s[70:71]
	s_mov_b32 m0, s29
	s_nop 0
	global_load_lds_dwordx4 v[68:69], off
	v_lshl_add_u64 v[68:69], v[42:43], 0, s[70:71]
	s_mov_b32 m0, s34
	s_nop 0
	global_load_lds_dwordx4 v[68:69], off
	v_lshl_add_u64 v[68:69], v[44:45], 0, s[70:71]
	s_mov_b32 m0, s41
	s_nop 0
	global_load_lds_dwordx4 v[68:69], off
	ds_read_b128 v[68:71], v0 offset:32768
	ds_read_b128 v[72:75], v50 offset:49152
	ds_read_b128 v[76:79], v50 offset:53248
	s_waitcnt lgkmcnt(0)
	v_mfma_f32_32x32x16_bf16 v[2:17], v[68:71], v[72:75], v[2:17]
	s_mov_b32 m0, s35
	v_mfma_f32_32x32x16_bf16 v[18:33], v[68:71], v[76:79], v[18:33]
	ds_read_b128 v[68:71], v48 offset:32768
	ds_read_b128 v[72:75], v49 offset:49152
	ds_read_b128 v[76:79], v49 offset:53248
	s_waitcnt lgkmcnt(1)
	v_mfma_f32_32x32x16_bf16 v[2:17], v[68:71], v[72:75], v[2:17]
	s_waitcnt lgkmcnt(0)
	v_mfma_f32_32x32x16_bf16 v[18:33], v[68:71], v[76:79], v[18:33]
	ds_read_b128 v[68:71], v52 offset:32768
	ds_read_b128 v[72:75], v51 offset:49152
	ds_read_b128 v[76:79], v51 offset:53248
	s_waitcnt lgkmcnt(1)
	v_mfma_f32_32x32x16_bf16 v[2:17], v[68:71], v[72:75], v[2:17]
	s_waitcnt lgkmcnt(0)
	v_mfma_f32_32x32x16_bf16 v[18:33], v[68:71], v[76:79], v[18:33]
	ds_read_b128 v[68:71], v54 offset:32768
	ds_read_b128 v[72:75], v53 offset:49152
	ds_read_b128 v[76:79], v53 offset:53248
	s_waitcnt vmcnt(0)
	s_waitcnt lgkmcnt(0)
	s_barrier
	v_mfma_f32_32x32x16_bf16 v[2:17], v[68:71], v[72:75], v[2:17]
	v_mfma_f32_32x32x16_bf16 v[18:33], v[68:71], v[76:79], v[18:33]
	v_lshl_add_u64 v[68:69], v[34:35], 0, s[72:73]
	global_load_lds_dwordx4 v[68:69], off
	v_lshl_add_u64 v[68:69], v[36:37], 0, s[72:73]
	s_mov_b32 m0, s36
	s_nop 0
	global_load_lds_dwordx4 v[68:69], off
	v_lshl_add_u64 v[68:69], v[40:41], 0, s[72:73]
	s_mov_b32 m0, s37
	s_nop 0
	global_load_lds_dwordx4 v[68:69], off
	v_lshl_add_u64 v[68:69], v[38:39], 0, s[72:73]
	s_mov_b32 m0, s40
	s_nop 0
	global_load_lds_dwordx4 v[68:69], off
	v_lshl_add_u64 v[68:69], v[42:43], 0, s[72:73]
	s_mov_b32 m0, s46
	s_nop 0
	global_load_lds_dwordx4 v[68:69], off
	v_lshl_add_u64 v[68:69], v[44:45], 0, s[72:73]
	s_mov_b32 m0, s47
	s_nop 0
	global_load_lds_dwordx4 v[68:69], off
	ds_read_b128 v[68:71], v0
	ds_read_b128 v[72:75], v50 offset:16384
	ds_read_b128 v[76:79], v50 offset:20480
	s_waitcnt lgkmcnt(0)
	v_mfma_f32_32x32x16_bf16 v[2:17], v[68:71], v[72:75], v[2:17]
	s_mov_b32 m0, s9
	v_mfma_f32_32x32x16_bf16 v[18:33], v[68:71], v[76:79], v[18:33]
	ds_read_b128 v[68:71], v48
	ds_read_b128 v[72:75], v49 offset:16384
	ds_read_b128 v[76:79], v49 offset:20480
	s_waitcnt lgkmcnt(1)
	v_mfma_f32_32x32x16_bf16 v[2:17], v[68:71], v[72:75], v[2:17]
	s_waitcnt lgkmcnt(0)
	v_mfma_f32_32x32x16_bf16 v[18:33], v[68:71], v[76:79], v[18:33]
	ds_read_b128 v[68:71], v52
	ds_read_b128 v[72:75], v51 offset:16384
	ds_read_b128 v[76:79], v51 offset:20480
	s_waitcnt lgkmcnt(1)
	v_mfma_f32_32x32x16_bf16 v[2:17], v[68:71], v[72:75], v[2:17]
	s_waitcnt lgkmcnt(0)
	v_mfma_f32_32x32x16_bf16 v[18:33], v[68:71], v[76:79], v[18:33]
	ds_read_b128 v[68:71], v54
	ds_read_b128 v[72:75], v53 offset:16384
	ds_read_b128 v[76:79], v53 offset:20480
	s_waitcnt vmcnt(0)
	s_waitcnt lgkmcnt(0)
	s_barrier
; #define MFMA(a, b, c) __builtin_amdgcn_mfma_f32_32x32x16_bf16((a), (b), (c), 0, 0, 0)
; template <int AI, int BI>
; DI void gemm_tile(const u16* __restrict__ A, int lda, const u16* __restrict__ B, int ldb, int nk, bool swap,
;                   f32x16 (&acc)[AI][BI], char* lds) {
;     ...
;   for (int kt = 0; kt < nk; ++kt) {
;     const char* cur = lds + (kt & 1) * 32768;
;     if (kt + 1 < nk) gemm_stage<AI, BI>(A + (kt + 1) * 64, lda, B + (kt + 1) * 64, ldb, lds + ((kt + 1) & 1) * 32768, tid);
; #pragma unroll
;     for (int ks = 0; ks < 4; ++ks) {
;       const int co = ((ks * 2 + h) ^ sw) << 4;
;       s16x8 fa[AI], fb[BI];
; #pragma unroll
;       for (int i = 0; i < AI; ++i) fa[i] = *(const s16x8*)(cur + offA + i * 4096 + co);
; #pragma unroll
;       for (int i = 0; i < BI; ++i) fb[i] = *(const s16x8*)(cur + offB + i * 4096 + co);
; #pragma unroll
;       for (int i = 0; i < AI; ++i)
; #pragma unroll
;         for (int j = 0; j < BI; ++j) acc[i][j] = MFMA(fa[i], fb[j], acc[i][j]);
;     }
;     asm volatile("s_waitcnt vmcnt(0)" ::: "memory");
;     __syncthreads();
;   }
	v_mfma_f32_32x32x16_bf16 v[2:17], v[68:71], v[72:75], v[2:17]
	v_mfma_f32_32x32x16_bf16 v[18:33], v[68:71], v[76:79], v[18:33]
	v_lshl_add_u64 v[68:69], v[34:35], 0, s[74:75]
	global_load_lds_dwordx4 v[68:69], off
	v_lshl_add_u64 v[68:69], v[36:37], 0, s[74:75]
	s_mov_b32 m0, s18
	s_nop 0
	global_load_lds_dwordx4 v[68:69], off
	v_lshl_add_u64 v[68:69], v[40:41], 0, s[74:75]
	s_mov_b32 m0, s28
	s_nop 0
	global_load_lds_dwordx4 v[68:69], off
	v_lshl_add_u64 v[68:69], v[38:39], 0, s[74:75]
	s_mov_b32 m0, s29
	s_nop 0
	global_load_lds_dwordx4 v[68:69], off
	v_lshl_add_u64 v[68:69], v[42:43], 0, s[74:75]
	s_mov_b32 m0, s34
	s_nop 0
	global_load_lds_dwordx4 v[68:69], off
	v_lshl_add_u64 v[68:69], v[44:45], 0, s[74:75]
	s_mov_b32 m0, s41
	s_nop 0
	global_load_lds_dwordx4 v[68:69], off
	ds_read_b128 v[68:71], v0 offset:32768
	ds_read_b128 v[72:75], v50 offset:49152
	ds_read_b128 v[76:79], v50 offset:53248
	s_waitcnt lgkmcnt(0)
	v_mfma_f32_32x32x16_bf16 v[2:17], v[68:71], v[72:75], v[2:17]
	s_mov_b32 m0, s35
	v_mfma_f32_32x32x16_bf16 v[18:33], v[68:71], v[76:79], v[18:33]
	ds_read_b128 v[68:71], v48 offset:32768
	ds_read_b128 v[72:75], v49 offset:49152
	ds_read_b128 v[76:79], v49 offset:53248
	s_waitcnt lgkmcnt(1)
	v_mfma_f32_32x32x16_bf16 v[2:17], v[68:71], v[72:75], v[2:17]
	s_waitcnt lgkmcnt(0)
	v_mfma_f32_32x32x16_bf16 v[18:33], v[68:71], v[76:79], v[18:33]
	ds_read_b128 v[68:71], v52 offset:32768
	ds_read_b128 v[72:75], v51 offset:49152
	ds_read_b128 v[76:79], v51 offset:53248
	s_waitcnt lgkmcnt(1)
	v_mfma_f32_32x32x16_bf16 v[2:17], v[68:71], v[72:75], v[2:17]
	s_waitcnt lgkmcnt(0)
	v_mfma_f32_32x32x16_bf16 v[18:33], v[68:71], v[76:79], v[18:33]
	ds_read_b128 v[68:71], v54 offset:32768
	ds_read_b128 v[72:75], v53 offset:49152
	ds_read_b128 v[76:79], v53 offset:53248
	s_waitcnt vmcnt(0)
	s_waitcnt lgkmcnt(0)
	s_barrier
	v_mfma_f32_32x32x16_bf16 v[2:17], v[68:71], v[72:75], v[2:17]
	v_mfma_f32_32x32x16_bf16 v[18:33], v[68:71], v[76:79], v[18:33]
	v_lshl_add_u64 v[68:69], v[34:35], 0, s[76:77]
	global_load_lds_dwordx4 v[68:69], off
	v_lshl_add_u64 v[68:69], v[36:37], 0, s[76:77]
	s_mov_b32 m0, s36
	s_nop 0
	global_load_lds_dwordx4 v[68:69], off
	v_lshl_add_u64 v[68:69], v[40:41], 0, s[76:77]
	s_mov_b32 m0, s37
	s_nop 0
	global_load_lds_dwordx4 v[68:69], off
	v_lshl_add_u64 v[68:69], v[38:39], 0, s[76:77]
	s_mov_b32 m0, s40
	s_nop 0
	global_load_lds_dwordx4 v[68:69], off
	v_lshl_add_u64 v[68:69], v[42:43], 0, s[76:77]
	s_mov_b32 m0, s46
	s_nop 0
	global_load_lds_dwordx4 v[68:69], off
	v_lshl_add_u64 v[68:69], v[44:45], 0, s[76:77]
	s_mov_b32 m0, s47
	s_nop 0
	global_load_lds_dwordx4 v[68:69], off
	ds_read_b128 v[68:71], v0
	ds_read_b128 v[72:75], v50 offset:16384
	ds_read_b128 v[76:79], v50 offset:20480
	s_waitcnt lgkmcnt(0)
	v_mfma_f32_32x32x16_bf16 v[2:17], v[68:71], v[72:75], v[2:17]
	s_mov_b32 m0, s9
	v_readfirstlane_b32 s9, v55
	v_and_b32_e32 v55, 31, v46
	v_mfma_f32_32x32x16_bf16 v[18:33], v[68:71], v[76:79], v[18:33]
	ds_read_b128 v[68:71], v48
	ds_read_b128 v[72:75], v49 offset:16384
	ds_read_b128 v[76:79], v49 offset:20480
	s_waitcnt lgkmcnt(1)
	v_mfma_f32_32x32x16_bf16 v[2:17], v[68:71], v[72:75], v[2:17]
	s_waitcnt lgkmcnt(0)
	v_mfma_f32_32x32x16_bf16 v[18:33], v[68:71], v[76:79], v[18:33]
	ds_read_b128 v[68:71], v52
	ds_read_b128 v[72:75], v51 offset:16384
	ds_read_b128 v[76:79], v51 offset:20480
	s_waitcnt lgkmcnt(1)
	v_mfma_f32_32x32x16_bf16 v[2:17], v[68:71], v[72:75], v[2:17]
	s_waitcnt lgkmcnt(0)
	v_mfma_f32_32x32x16_bf16 v[18:33], v[68:71], v[76:79], v[18:33]
	ds_read_b128 v[68:71], v54
	ds_read_b128 v[72:75], v53 offset:16384
	ds_read_b128 v[76:79], v53 offset:20480
	s_waitcnt vmcnt(0)
	s_waitcnt lgkmcnt(0)
	s_barrier
	v_mfma_f32_32x32x16_bf16 v[2:17], v[68:71], v[72:75], v[2:17]
	v_mfma_f32_32x32x16_bf16 v[18:33], v[68:71], v[76:79], v[18:33]
	v_lshl_add_u64 v[68:69], v[34:35], 0, s[80:81]
	global_load_lds_dwordx4 v[68:69], off
	v_lshl_add_u64 v[68:69], v[36:37], 0, s[80:81]
	s_mov_b32 m0, s18
	v_readfirstlane_b32 s18, v56
	global_load_lds_dwordx4 v[68:69], off
	v_lshl_add_u64 v[68:69], v[40:41], 0, s[80:81]
	s_mov_b32 m0, s28
	v_readfirstlane_b32 s28, v57
	global_load_lds_dwordx4 v[68:69], off
	v_lshl_add_u64 v[68:69], v[38:39], 0, s[80:81]
	s_mov_b32 m0, s29
	v_readfirstlane_b32 s29, v59
	global_load_lds_dwordx4 v[68:69], off
	v_lshl_add_u64 v[68:69], v[42:43], 0, s[80:81]
	s_mov_b32 m0, s34
	v_lshl_add_u64 v[56:57], v[38:39], 0, s[84:85]
	global_load_lds_dwordx4 v[68:69], off
	v_lshl_add_u64 v[68:69], v[44:45], 0, s[80:81]
	s_mov_b32 m0, s41
	v_readfirstlane_b32 s34, v65
	global_load_lds_dwordx4 v[68:69], off
	ds_read_b128 v[68:71], v0 offset:32768
	ds_read_b128 v[72:75], v50 offset:49152
	ds_read_b128 v[76:79], v50 offset:53248
	s_waitcnt lgkmcnt(0)
	v_mfma_f32_32x32x16_bf16 v[2:17], v[68:71], v[72:75], v[2:17]
	s_mov_b32 m0, s35
	v_readfirstlane_b32 s35, v66
	v_readfirstlane_b32 s41, v60
	v_mfma_f32_32x32x16_bf16 v[18:33], v[68:71], v[76:79], v[18:33]
	ds_read_b128 v[68:71], v48 offset:32768
	ds_read_b128 v[72:75], v49 offset:49152
	ds_read_b128 v[76:79], v49 offset:53248
	s_waitcnt lgkmcnt(1)
	v_mfma_f32_32x32x16_bf16 v[2:17], v[68:71], v[72:75], v[2:17]
	s_waitcnt lgkmcnt(0)
	v_mfma_f32_32x32x16_bf16 v[18:33], v[68:71], v[76:79], v[18:33]
	ds_read_b128 v[68:71], v52 offset:32768
	ds_read_b128 v[72:75], v51 offset:49152
	ds_read_b128 v[76:79], v51 offset:53248
	s_waitcnt lgkmcnt(1)
	v_mfma_f32_32x32x16_bf16 v[2:17], v[68:71], v[72:75], v[2:17]
	s_waitcnt lgkmcnt(0)
	v_mfma_f32_32x32x16_bf16 v[18:33], v[68:71], v[76:79], v[18:33]
	ds_read_b128 v[68:71], v54 offset:32768
	ds_read_b128 v[72:75], v53 offset:49152
	ds_read_b128 v[76:79], v53 offset:53248
	s_waitcnt vmcnt(0)
	s_waitcnt lgkmcnt(0)
	s_barrier
; #define MFMA(a, b, c) __builtin_amdgcn_mfma_f32_32x32x16_bf16((a), (b), (c), 0, 0, 0)
; template <int AI, int BI>
; DI void gemm_tile(const u16* __restrict__ A, int lda, const u16* __restrict__ B, int ldb, int nk, bool swap,
;                   f32x16 (&acc)[AI][BI], char* lds) {
;     ...
;   for (int kt = 0; kt < nk; ++kt) {
;     const char* cur = lds + (kt & 1) * 32768;
;     if (kt + 1 < nk) gemm_stage<AI, BI>(A + (kt + 1) * 64, lda, B + (kt + 1) * 64, ldb, lds + ((kt + 1) & 1) * 32768, tid);
; #pragma unroll
;     for (int ks = 0; ks < 4; ++ks) {
;       const int co = ((ks * 2 + h) ^ sw) << 4;
;       s16x8 fa[AI], fb[BI];
; #pragma unroll
;       for (int i = 0; i < AI; ++i) fa[i] = *(const s16x8*)(cur + offA + i * 4096 + co);
; #pragma unroll
;       for (int i = 0; i < BI; ++i) fb[i] = *(const s16x8*)(cur + offB + i * 4096 + co);
; #pragma unroll
;       for (int i = 0; i < AI; ++i)
; #pragma unroll
;         for (int j = 0; j < BI; ++j) acc[i][j] = MFMA(fa[i], fb[j], acc[i][j]);
;     }
;     asm volatile("s_waitcnt vmcnt(0)" ::: "memory");
;     __syncthreads();
;   }
	v_mfma_f32_32x32x16_bf16 v[2:17], v[68:71], v[72:75], v[2:17]
	v_mfma_f32_32x32x16_bf16 v[18:33], v[68:71], v[76:79], v[18:33]
	v_lshl_add_u64 v[68:69], v[34:35], 0, s[82:83]
	global_load_lds_dwordx4 v[68:69], off
	v_lshl_add_u64 v[68:69], v[36:37], 0, s[82:83]
	s_mov_b32 m0, s36
	v_readfirstlane_b32 s36, v64
	global_load_lds_dwordx4 v[68:69], off
	v_lshl_add_u64 v[68:69], v[40:41], 0, s[82:83]
	s_mov_b32 m0, s37
	v_readfirstlane_b32 s37, v61
	global_load_lds_dwordx4 v[68:69], off
	v_lshl_add_u64 v[68:69], v[38:39], 0, s[82:83]
	s_mov_b32 m0, s40
	v_readfirstlane_b32 s40, v58
	global_load_lds_dwordx4 v[68:69], off
	v_lshl_add_u64 v[68:69], v[42:43], 0, s[82:83]
	s_mov_b32 m0, s46
	v_readfirstlane_b32 s46, v62
	global_load_lds_dwordx4 v[68:69], off
	v_lshl_add_u64 v[68:69], v[44:45], 0, s[82:83]
	s_mov_b32 m0, s47
	v_readfirstlane_b32 s47, v63
	global_load_lds_dwordx4 v[68:69], off
	ds_read_b128 v[68:71], v0
	ds_read_b128 v[72:75], v50 offset:16384
	ds_read_b128 v[76:79], v50 offset:20480
	s_waitcnt lgkmcnt(0)
	v_mfma_f32_32x32x16_bf16 v[2:17], v[68:71], v[72:75], v[2:17]
	s_mov_b32 m0, s9
	v_mfma_f32_32x32x16_bf16 v[18:33], v[68:71], v[76:79], v[18:33]
	ds_read_b128 v[68:71], v48
	ds_read_b128 v[72:75], v49 offset:16384
	ds_read_b128 v[76:79], v49 offset:20480
	s_waitcnt lgkmcnt(1)
	v_mfma_f32_32x32x16_bf16 v[2:17], v[68:71], v[72:75], v[2:17]
	s_waitcnt lgkmcnt(0)
	v_mfma_f32_32x32x16_bf16 v[18:33], v[68:71], v[76:79], v[18:33]
	ds_read_b128 v[68:71], v52
	ds_read_b128 v[72:75], v51 offset:16384
	ds_read_b128 v[76:79], v51 offset:20480
	s_waitcnt lgkmcnt(1)
	v_mfma_f32_32x32x16_bf16 v[2:17], v[68:71], v[72:75], v[2:17]
	s_waitcnt lgkmcnt(0)
	v_mfma_f32_32x32x16_bf16 v[18:33], v[68:71], v[76:79], v[18:33]
	ds_read_b128 v[68:71], v54
	ds_read_b128 v[72:75], v53 offset:16384
	ds_read_b128 v[76:79], v53 offset:20480
	s_waitcnt vmcnt(0)
	s_waitcnt lgkmcnt(0)
	s_barrier
	v_mfma_f32_32x32x16_bf16 v[2:17], v[68:71], v[72:75], v[2:17]
	v_mfma_f32_32x32x16_bf16 v[18:33], v[68:71], v[76:79], v[18:33]
	v_lshl_add_u64 v[68:69], v[34:35], 0, s[84:85]
	global_load_lds_dwordx4 v[68:69], off
	v_lshl_add_u64 v[68:69], v[36:37], 0, s[84:85]
	s_mov_b32 m0, s18
	s_nop 0
	global_load_lds_dwordx4 v[68:69], off
	v_lshl_add_u64 v[68:69], v[40:41], 0, s[84:85]
	s_mov_b32 m0, s28
	s_nop 0
	global_load_lds_dwordx4 v[68:69], off
	s_mov_b32 m0, s29
	s_nop 0
	global_load_lds_dwordx4 v[56:57], off
	v_lshl_add_u64 v[56:57], v[42:43], 0, s[84:85]
	s_mov_b32 m0, s34
	s_nop 0
	global_load_lds_dwordx4 v[56:57], off
	v_lshl_add_u64 v[56:57], v[44:45], 0, s[84:85]
	s_mov_b32 m0, s35
	s_nop 0
	global_load_lds_dwordx4 v[56:57], off
	ds_read_b128 v[66:69], v0 offset:32768
	ds_read_b128 v[70:73], v50 offset:49152
	ds_read_b128 v[74:77], v50 offset:53248
	s_waitcnt lgkmcnt(0)
	v_mfma_f32_32x32x16_bf16 v[2:17], v[66:69], v[70:73], v[2:17]
	v_lshl_add_u64 v[56:57], v[34:35], 0, s[78:79]
	s_mov_b32 m0, s36
	v_mfma_f32_32x32x16_bf16 v[18:33], v[66:69], v[74:77], v[18:33]
	ds_read_b128 v[66:69], v48 offset:32768
	ds_read_b128 v[70:73], v49 offset:49152
	ds_read_b128 v[74:77], v49 offset:53248
	s_waitcnt lgkmcnt(1)
	v_mfma_f32_32x32x16_bf16 v[2:17], v[66:69], v[70:73], v[2:17]
	s_waitcnt lgkmcnt(0)
	v_mfma_f32_32x32x16_bf16 v[18:33], v[66:69], v[74:77], v[18:33]
	ds_read_b128 v[66:69], v52 offset:32768
	ds_read_b128 v[70:73], v51 offset:49152
	ds_read_b128 v[74:77], v51 offset:53248
	s_waitcnt lgkmcnt(1)
	v_mfma_f32_32x32x16_bf16 v[2:17], v[66:69], v[70:73], v[2:17]
	s_waitcnt lgkmcnt(0)
	v_mfma_f32_32x32x16_bf16 v[18:33], v[66:69], v[74:77], v[18:33]
	ds_read_b128 v[66:69], v54 offset:32768
	ds_read_b128 v[70:73], v53 offset:49152
	ds_read_b128 v[74:77], v53 offset:53248
	s_waitcnt vmcnt(0)
	s_waitcnt lgkmcnt(0)
	s_barrier
	global_load_lds_dwordx4 v[56:57], off
	v_lshl_add_u64 v[56:57], v[36:37], 0, s[78:79]
	s_mov_b32 m0, s37
	v_mfma_f32_32x32x16_bf16 v[2:17], v[66:69], v[70:73], v[2:17]
	global_load_lds_dwordx4 v[56:57], off
	v_lshl_add_u64 v[56:57], v[40:41], 0, s[78:79]
	s_mov_b32 m0, s40
	s_nop 0
	global_load_lds_dwordx4 v[56:57], off
	v_lshl_add_u64 v[56:57], v[38:39], 0, s[78:79]
	s_mov_b32 m0, s41
	v_mfma_f32_32x32x16_bf16 v[18:33], v[66:69], v[74:77], v[18:33]
	global_load_lds_dwordx4 v[56:57], off
	v_lshl_add_u64 v[56:57], v[42:43], 0, s[78:79]
	s_mov_b32 m0, s46
	s_nop 0
	global_load_lds_dwordx4 v[56:57], off
	v_lshl_add_u64 v[56:57], v[44:45], 0, s[78:79]
	s_mov_b32 m0, s47
	s_nop 0
	global_load_lds_dwordx4 v[56:57], off
	ds_read_b128 v[56:59], v0
	ds_read_b128 v[60:63], v50 offset:16384
	ds_read_b128 v[64:67], v50 offset:20480
	s_waitcnt lgkmcnt(0)
	v_mfma_f32_32x32x16_bf16 v[2:17], v[56:59], v[60:63], v[2:17]
	s_mov_b32 m0, s9
	v_mfma_f32_32x32x16_bf16 v[18:33], v[56:59], v[64:67], v[18:33]
	ds_read_b128 v[56:59], v48
	ds_read_b128 v[60:63], v49 offset:16384
	ds_read_b128 v[64:67], v49 offset:20480
	s_waitcnt lgkmcnt(1)
	v_mfma_f32_32x32x16_bf16 v[2:17], v[56:59], v[60:63], v[2:17]
	s_waitcnt lgkmcnt(0)
	v_mfma_f32_32x32x16_bf16 v[18:33], v[56:59], v[64:67], v[18:33]
	ds_read_b128 v[56:59], v52
	ds_read_b128 v[60:63], v51 offset:16384
	ds_read_b128 v[64:67], v51 offset:20480
	s_waitcnt lgkmcnt(1)
	v_mfma_f32_32x32x16_bf16 v[2:17], v[56:59], v[60:63], v[2:17]
	s_waitcnt lgkmcnt(0)
	v_mfma_f32_32x32x16_bf16 v[18:33], v[56:59], v[64:67], v[18:33]
	ds_read_b128 v[56:59], v54
	ds_read_b128 v[60:63], v53 offset:16384
	ds_read_b128 v[64:67], v53 offset:20480
	s_waitcnt vmcnt(0)
	s_waitcnt lgkmcnt(0)
	s_barrier
; #define MFMA(a, b, c) __builtin_amdgcn_mfma_f32_32x32x16_bf16((a), (b), (c), 0, 0, 0)
; template <int AI, int BI>
; DI void gemm_tile(const u16* __restrict__ A, int lda, const u16* __restrict__ B, int ldb, int nk, bool swap,
;                   f32x16 (&acc)[AI][BI], char* lds) {
;     ...
;   for (int kt = 0; kt < nk; ++kt) {
;     const char* cur = lds + (kt & 1) * 32768;
;     if (kt + 1 < nk) gemm_stage<AI, BI>(A + (kt + 1) * 64, lda, B + (kt + 1) * 64, ldb, lds + ((kt + 1) & 1) * 32768, tid);
; #pragma unroll
;     for (int ks = 0; ks < 4; ++ks) {
;       const int co = ((ks * 2 + h) ^ sw) << 4;
;       s16x8 fa[AI], fb[BI];
; #pragma unroll
;       for (int i = 0; i < AI; ++i) fa[i] = *(const s16x8*)(cur + offA + i * 4096 + co);
; #pragma unroll
;       for (int i = 0; i < BI; ++i) fb[i] = *(const s16x8*)(cur + offB + i * 4096 + co);
; #pragma unroll
;       for (int i = 0; i < AI; ++i)
; #pragma unroll
;         for (int j = 0; j < BI; ++j) acc[i][j] = MFMA(fa[i], fb[j], acc[i][j]);
;     }
;     asm volatile("s_waitcnt vmcnt(0)" ::: "memory");
;     __syncthreads();
;   }
	v_mfma_f32_32x32x16_bf16 v[2:17], v[56:59], v[60:63], v[2:17]
	v_mfma_f32_32x32x16_bf16 v[18:33], v[56:59], v[64:67], v[18:33]
	v_lshl_add_u64 v[56:57], v[34:35], 0, s[2:3]
	global_load_lds_dwordx4 v[56:57], off
	v_lshl_add_u64 v[56:57], v[36:37], 0, s[2:3]
	s_mov_b32 m0, s18
	v_lshl_add_u64 v[34:35], v[34:35], 0, s[30:31]
	global_load_lds_dwordx4 v[56:57], off
	v_lshl_add_u64 v[56:57], v[40:41], 0, s[2:3]
	s_mov_b32 m0, s28
	s_nop 0
	global_load_lds_dwordx4 v[56:57], off
	v_lshl_add_u64 v[56:57], v[38:39], 0, s[2:3]
	s_mov_b32 m0, s29
	s_nop 0
	global_load_lds_dwordx4 v[56:57], off
	v_lshl_add_u64 v[56:57], v[42:43], 0, s[2:3]
	s_mov_b32 m0, s34
	s_nop 0
	global_load_lds_dwordx4 v[56:57], off
	v_lshl_add_u64 v[56:57], v[44:45], 0, s[2:3]
	s_mov_b32 m0, s35
	s_nop 0
	global_load_lds_dwordx4 v[56:57], off
	ds_read_b128 v[56:59], v0 offset:32768
	ds_read_b128 v[60:63], v50 offset:49152
	ds_read_b128 v[64:67], v50 offset:53248
	s_waitcnt lgkmcnt(0)
	v_mfma_f32_32x32x16_bf16 v[2:17], v[56:59], v[60:63], v[2:17]
	s_mov_b32 m0, s36
	v_mfma_f32_32x32x16_bf16 v[18:33], v[56:59], v[64:67], v[18:33]
	ds_read_b128 v[56:59], v48 offset:32768
	ds_read_b128 v[60:63], v49 offset:49152
	ds_read_b128 v[64:67], v49 offset:53248
	s_waitcnt lgkmcnt(1)
	v_mfma_f32_32x32x16_bf16 v[2:17], v[56:59], v[60:63], v[2:17]
	s_waitcnt lgkmcnt(0)
	v_mfma_f32_32x32x16_bf16 v[18:33], v[56:59], v[64:67], v[18:33]
	ds_read_b128 v[56:59], v52 offset:32768
	ds_read_b128 v[60:63], v51 offset:49152
	ds_read_b128 v[64:67], v51 offset:53248
	s_waitcnt lgkmcnt(1)
	v_mfma_f32_32x32x16_bf16 v[2:17], v[56:59], v[60:63], v[2:17]
	s_waitcnt lgkmcnt(0)
	v_mfma_f32_32x32x16_bf16 v[18:33], v[56:59], v[64:67], v[18:33]
	ds_read_b128 v[56:59], v54 offset:32768
	ds_read_b128 v[60:63], v53 offset:49152
	ds_read_b128 v[64:67], v53 offset:53248
	s_waitcnt vmcnt(0)
	s_waitcnt lgkmcnt(0)
	s_barrier
	global_load_lds_dwordx4 v[34:35], off
	v_lshl_add_u64 v[34:35], v[36:37], 0, s[30:31]
	s_mov_b32 m0, s37
	v_mfma_f32_32x32x16_bf16 v[2:17], v[56:59], v[60:63], v[2:17]
	global_load_lds_dwordx4 v[34:35], off
	v_lshl_add_u64 v[34:35], v[40:41], 0, s[30:31]
	s_mov_b32 m0, s40
	s_nop 0
	global_load_lds_dwordx4 v[34:35], off
	v_lshl_add_u64 v[34:35], v[38:39], 0, s[30:31]
	s_mov_b32 m0, s41
	v_mfma_f32_32x32x16_bf16 v[18:33], v[56:59], v[64:67], v[18:33]
	global_load_lds_dwordx4 v[34:35], off
	v_lshl_add_u64 v[34:35], v[42:43], 0, s[30:31]
	s_mov_b32 m0, s46
	s_nop 0
	global_load_lds_dwordx4 v[34:35], off
	v_lshl_add_u64 v[34:35], v[44:45], 0, s[30:31]
	s_mov_b32 m0, s47
	s_nop 0
	global_load_lds_dwordx4 v[34:35], off
	ds_read_b128 v[34:37], v0
	ds_read_b128 v[38:41], v50 offset:16384
	ds_read_b128 v[42:45], v50 offset:20480
	s_waitcnt lgkmcnt(0)
	v_mfma_f32_32x32x16_bf16 v[2:17], v[34:37], v[38:41], v[2:17]
	v_mfma_f32_32x32x16_bf16 v[18:33], v[34:37], v[42:45], v[18:33]
	ds_read_b128 v[34:37], v48
	ds_read_b128 v[38:41], v49 offset:16384
	ds_read_b128 v[42:45], v49 offset:20480
	s_waitcnt lgkmcnt(1)
	v_mfma_f32_32x32x16_bf16 v[2:17], v[34:37], v[38:41], v[2:17]
	s_waitcnt lgkmcnt(0)
	v_mfma_f32_32x32x16_bf16 v[18:33], v[34:37], v[42:45], v[18:33]
	ds_read_b128 v[34:37], v52
	ds_read_b128 v[38:41], v51 offset:16384
	ds_read_b128 v[42:45], v51 offset:20480
	s_waitcnt lgkmcnt(1)
	v_mfma_f32_32x32x16_bf16 v[2:17], v[34:37], v[38:41], v[2:17]
	s_waitcnt lgkmcnt(0)
	v_mfma_f32_32x32x16_bf16 v[18:33], v[34:37], v[42:45], v[18:33]
	ds_read_b128 v[34:37], v54
	ds_read_b128 v[38:41], v53 offset:16384
	ds_read_b128 v[42:45], v53 offset:20480
	s_waitcnt vmcnt(0)
	s_waitcnt lgkmcnt(0)
	s_barrier
	v_mfma_f32_32x32x16_bf16 v[2:17], v[34:37], v[38:41], v[2:17]
	v_mfma_f32_32x32x16_bf16 v[18:33], v[34:37], v[42:45], v[18:33]
	ds_read_b128 v[34:37], v50 offset:53248
	ds_read_b128 v[38:41], v50 offset:49152
	ds_read_b128 v[42:45], v0 offset:32768
	v_mov_b32_e32 v0, v1
	s_waitcnt lgkmcnt(0)
	v_mfma_f32_32x32x16_bf16 v[2:17], v[42:45], v[38:41], v[2:17]
	v_mfma_f32_32x32x16_bf16 v[18:33], v[42:45], v[34:37], v[18:33]
	ds_read_b128 v[34:37], v48 offset:32768
	ds_read_b128 v[38:41], v49 offset:49152
	ds_read_b128 v[42:45], v49 offset:53248
	s_waitcnt lgkmcnt(1)
	v_mfma_f32_32x32x16_bf16 v[2:17], v[34:37], v[38:41], v[2:17]
	s_waitcnt lgkmcnt(0)
	v_mfma_f32_32x32x16_bf16 v[18:33], v[34:37], v[42:45], v[18:33]
	ds_read_b128 v[34:37], v52 offset:32768
	ds_read_b128 v[38:41], v51 offset:49152
	ds_read_b128 v[42:45], v51 offset:53248
	s_waitcnt lgkmcnt(1)
	v_mfma_f32_32x32x16_bf16 v[2:17], v[34:37], v[38:41], v[2:17]
	s_waitcnt lgkmcnt(0)
	v_mfma_f32_32x32x16_bf16 v[18:33], v[34:37], v[42:45], v[18:33]
	ds_read_b128 v[34:37], v54 offset:32768
	ds_read_b128 v[38:41], v53 offset:49152
	ds_read_b128 v[42:45], v53 offset:53248
	s_waitcnt vmcnt(0)
	s_waitcnt lgkmcnt(0)
	s_barrier
; #define GAS __attribute__((address_space(1)))
; DI int opaque0() { int z = 0; asm volatile("" : "+v"(z)); return z; }
; DI void xcd_barrier(const XcdBarrier& b) {
;   asm volatile("s_waitcnt vmcnt(0)" ::: "memory");
;   __syncthreads();
;   if (threadIdx.x == 0) {
;     unsigned* bar = b.bar;
;     __builtin_amdgcn_s_waitcnt(0);
;     unsigned nloc = b.st[0], nx = b.st[1];
;     if (nloc == 0u) { xcd_barrier_complete(bar, b.x, nloc, nx); b.st[0] = nloc; b.st[1] = nx; }
; template <int AI>
; DI void gu_tile(char* wsb, int sub, int m0, int n0, char* lds) {
;     ...
;   const int m0e = m0 + opaque0();
;   const int hc = (n0 >> 1) + wb * 32 + r;
;   GAS u16* HIDu = uptr(HID);
;   const unsigned ib = (unsigned)((m0e + wa * 32 * AI + 4 * h) * 2816 + hc);
; #pragma unroll
;   for (int ai = 0; ai < AI; ++ai)
; #pragma unroll
;     for (int reg = 0; reg < 16; ++reg) {
;       float g = acc[ai][0][reg], u = acc[ai][1][reg];
;       float v = g * __builtin_amdgcn_rcpf(1.f + __expf(-g)) * u;
;       HIDu[ib + (unsigned)((ai * 32 + (reg & 3) + 8 * (reg >> 2)) * 2816)] = f2bf(v);
;       if ((reg & 7) == 7) __builtin_amdgcn_sched_barrier(0);
;     }
	v_mfma_f32_32x32x16_bf16 v[2:17], v[34:37], v[38:41], v[2:17]
	v_mfma_f32_32x32x16_bf16 v[18:33], v[34:37], v[42:45], v[18:33]
	v_lshrrev_b32_e32 v36, 3, v46
	v_lshrrev_b32_e32 v34, 1, v47
	v_lshrrev_b32_e32 v35, 2, v47
	v_and_b32_e32 v36, 4, v36
	v_and_b32_e32 v34, 32, v34
	v_and_or_b32 v35, v35, s53, v36
	v_add3_u32 v35, v35, s17, v0
	v_or3_b32 v0, v34, v55, s8
	s_nop 2
	v_mul_f32_e32 v34, 0xbfb8aa3b, v2
	v_exp_f32_e32 v34, v34
	s_nop 0
	v_add_f32_e32 v34, 1.0, v34
	v_rcp_f32_e32 v34, v34
	s_nop 0
	v_mul_f32_e32 v2, v2, v34
	v_mad_u64_u32 v[34:35], s[8:9], v35, s51, v[0:1]
	v_mul_f32_e32 v0, 0xbfb8aa3b, v3
	v_exp_f32_e32 v0, v0
	v_mul_f32_e32 v2, v18, v2
	v_mov_b32_e32 v35, v1
	v_cvt_pk_bf16_f32 v2, v2, s0
	v_add_f32_e32 v0, 1.0, v0
	v_rcp_f32_e32 v0, v0
	v_lshl_add_u64 v[36:37], v[34:35], 1, s[6:7]
	global_store_short v[36:37], v2, off
	v_mul_f32_e32 v0, v3, v0
	v_mul_f32_e32 v0, v19, v0
	v_cvt_pk_bf16_f32 v18, v0, s0
	v_add_u32_e32 v0, 0xb00, v34
	v_lshl_add_u64 v[2:3], v[0:1], 1, s[6:7]
	v_mul_f32_e32 v0, 0xbfb8aa3b, v4
	v_exp_f32_e32 v0, v0
	global_store_short v[2:3], v18, off
	v_add_f32_e32 v0, 1.0, v0
	v_rcp_f32_e32 v0, v0
	s_nop 0
	v_mul_f32_e32 v0, v4, v0
	v_mul_f32_e32 v0, v20, v0
	v_cvt_pk_bf16_f32 v4, v0, s0
	v_add_u32_e32 v0, 0x1600, v34
	v_lshl_add_u64 v[2:3], v[0:1], 1, s[6:7]
	v_mul_f32_e32 v0, 0xbfb8aa3b, v5
	v_exp_f32_e32 v0, v0
	global_store_short v[2:3], v4, off
	v_add_f32_e32 v0, 1.0, v0
	v_rcp_f32_e32 v0, v0
	s_nop 0
	v_mul_f32_e32 v0, v5, v0
	v_mul_f32_e32 v0, v21, v0
	v_cvt_pk_bf16_f32 v4, v0, s0
	v_add_u32_e32 v0, 0x2100, v34
	v_lshl_add_u64 v[2:3], v[0:1], 1, s[6:7]
	v_mul_f32_e32 v0, 0xbfb8aa3b, v6
	v_exp_f32_e32 v0, v0
	global_store_short v[2:3], v4, off
	v_add_f32_e32 v0, 1.0, v0
	v_rcp_f32_e32 v0, v0
	s_nop 0
	v_mul_f32_e32 v0, v6, v0
	v_mul_f32_e32 v0, v22, v0
	v_cvt_pk_bf16_f32 v4, v0, s0
	v_add_u32_e32 v0, 0x5800, v34
	v_lshl_add_u64 v[2:3], v[0:1], 1, s[6:7]
	v_mul_f32_e32 v0, 0xbfb8aa3b, v7
	v_exp_f32_e32 v0, v0
	global_store_short v[2:3], v4, off
	v_add_f32_e32 v0, 1.0, v0
	v_rcp_f32_e32 v0, v0
	s_nop 0
	v_mul_f32_e32 v0, v7, v0
	v_mul_f32_e32 v0, v23, v0
	v_cvt_pk_bf16_f32 v4, v0, s0
	v_add_u32_e32 v0, 0x6300, v34
	v_lshl_add_u64 v[2:3], v[0:1], 1, s[6:7]
	v_mul_f32_e32 v0, 0xbfb8aa3b, v8
	v_exp_f32_e32 v0, v0
	global_store_short v[2:3], v4, off
	v_add_f32_e32 v0, 1.0, v0
	v_rcp_f32_e32 v0, v0
	s_nop 0
	v_mul_f32_e32 v0, v8, v0
	v_mul_f32_e32 v0, v24, v0
	v_cvt_pk_bf16_f32 v4, v0, s0
	v_add_u32_e32 v0, 0x6e00, v34
	v_lshl_add_u64 v[2:3], v[0:1], 1, s[6:7]
	v_mul_f32_e32 v0, 0xbfb8aa3b, v9
	v_exp_f32_e32 v0, v0
	global_store_short v[2:3], v4, off
	v_add_f32_e32 v0, 1.0, v0
	v_rcp_f32_e32 v0, v0
	s_nop 0
	v_mul_f32_e32 v0, v9, v0
	v_mul_f32_e32 v0, v25, v0
	v_cvt_pk_bf16_f32 v4, v0, s0
	v_add_u32_e32 v0, 0x7900, v34
	v_lshl_add_u64 v[2:3], v[0:1], 1, s[6:7]
	global_store_short v[2:3], v4, off
	v_mul_f32_e32 v0, 0xbfb8aa3b, v10
	v_exp_f32_e32 v0, v0
	s_nop 0
	v_add_f32_e32 v0, 1.0, v0
	v_rcp_f32_e32 v0, v0
	s_nop 0
	v_mul_f32_e32 v0, v10, v0
	v_mul_f32_e32 v0, v26, v0
	v_cvt_pk_bf16_f32 v4, v0, s0
	v_add_u32_e32 v0, 0xb000, v34
	v_lshl_add_u64 v[2:3], v[0:1], 1, s[6:7]
	v_mul_f32_e32 v0, 0xbfb8aa3b, v11
	v_exp_f32_e32 v0, v0
	global_store_short v[2:3], v4, off
	v_add_f32_e32 v0, 1.0, v0
	v_rcp_f32_e32 v0, v0
	s_nop 0
	v_mul_f32_e32 v0, v11, v0
	v_mul_f32_e32 v0, v27, v0
	v_cvt_pk_bf16_f32 v4, v0, s0
	v_add_u32_e32 v0, 0xbb00, v34
	v_lshl_add_u64 v[2:3], v[0:1], 1, s[6:7]
	v_mul_f32_e32 v0, 0xbfb8aa3b, v12
	v_exp_f32_e32 v0, v0
	global_store_short v[2:3], v4, off
	v_add_f32_e32 v0, 1.0, v0
	v_rcp_f32_e32 v0, v0
	s_nop 0
	v_mul_f32_e32 v0, v12, v0
	v_mul_f32_e32 v0, v28, v0
	v_cvt_pk_bf16_f32 v4, v0, s0
	v_add_u32_e32 v0, 0xc600, v34
	v_lshl_add_u64 v[2:3], v[0:1], 1, s[6:7]
	v_mul_f32_e32 v0, 0xbfb8aa3b, v13
	v_exp_f32_e32 v0, v0
	global_store_short v[2:3], v4, off
	v_add_f32_e32 v0, 1.0, v0
	v_rcp_f32_e32 v0, v0
	s_nop 0
	v_mul_f32_e32 v0, v13, v0
	v_mul_f32_e32 v0, v29, v0
	v_cvt_pk_bf16_f32 v4, v0, s0
	v_add_u32_e32 v0, 0xd100, v34
	v_lshl_add_u64 v[2:3], v[0:1], 1, s[6:7]
	v_mul_f32_e32 v0, 0xbfb8aa3b, v14
	v_exp_f32_e32 v0, v0
	global_store_short v[2:3], v4, off
	v_add_f32_e32 v0, 1.0, v0
	v_rcp_f32_e32 v0, v0
	s_nop 0
	v_mul_f32_e32 v0, v14, v0
	v_mul_f32_e32 v0, v30, v0
	v_cvt_pk_bf16_f32 v4, v0, s0
	v_add_u32_e32 v0, 0x10800, v34
	v_lshl_add_u64 v[2:3], v[0:1], 1, s[6:7]
	v_mul_f32_e32 v0, 0xbfb8aa3b, v15
	v_exp_f32_e32 v0, v0
	global_store_short v[2:3], v4, off
	v_add_f32_e32 v0, 1.0, v0
	v_rcp_f32_e32 v0, v0
	s_nop 0
	v_mul_f32_e32 v0, v15, v0
	v_mul_f32_e32 v0, v31, v0
	v_cvt_pk_bf16_f32 v4, v0, s0
	v_add_u32_e32 v0, 0x11300, v34
	v_lshl_add_u64 v[2:3], v[0:1], 1, s[6:7]
	v_mul_f32_e32 v0, 0xbfb8aa3b, v16
	v_exp_f32_e32 v0, v0
	global_store_short v[2:3], v4, off
	v_add_f32_e32 v0, 1.0, v0
	v_rcp_f32_e32 v0, v0
	s_nop 0
	v_mul_f32_e32 v0, v16, v0
	v_mul_f32_e32 v0, v32, v0
	v_cvt_pk_bf16_f32 v4, v0, s0
	v_add_u32_e32 v0, 0x11e00, v34
	v_lshl_add_u64 v[2:3], v[0:1], 1, s[6:7]
	v_mul_f32_e32 v0, 0xbfb8aa3b, v17
	v_exp_f32_e32 v0, v0
	global_store_short v[2:3], v4, off
	v_add_f32_e32 v0, 1.0, v0
	v_rcp_f32_e32 v0, v0
	s_nop 0
	v_mul_f32_e32 v0, v17, v0
	v_mul_f32_e32 v0, v33, v0
	v_cvt_pk_bf16_f32 v4, v0, s0
	v_add_u32_e32 v0, 0x12900, v34
	v_lshl_add_u64 v[2:3], v[0:1], 1, s[6:7]
	global_store_short v[2:3], v4, off
	s_add_i32 s16, s16, s49
	s_add_i32 s15, s15, s50
	s_add_i32 s14, s14, s48
	s_cmpk_gt_u32 s14, 0x57f
	s_cbranch_scc0 .LBB0_1210
.Lgc2_exit:
	v_readlane_b32 s28, v243, 45
	v_readlane_b32 s34, v243, 47
	v_readlane_b32 s29, v243, 46
	v_readlane_b32 s35, v243, 48
.LBB0_1212:
	s_waitcnt vmcnt(0)
	s_barrier
	s_and_saveexec_b64 s[6:7], s[90:91]
	v_readlane_b32 s48, v242, 11
	v_readlane_b32 s49, v242, 12
	s_cbranch_execz .LBB0_1260
	s_waitcnt vmcnt(0) expcnt(0) lgkmcnt(0)
	ds_read_b32 v3, v180
	ds_read_b32 v2, v181
	s_waitcnt lgkmcnt(1)
	v_cmp_ne_u32_e32 vcc, 0, v3
	s_cbranch_vccnz .LBB0_1228
	s_mov_b32 s14, 1
	s_branch .LBB0_1216
